# w_in projection epilogue: plain, silu, scaled and gate column tiles get straight-line code (one address set-up, packed f32 math, lane permutes of the next store issued before the wait)
# speedup vs baseline: 1.0124x; 1.0038x over previous
; #define GAS __attribute__((address_space(1)))
; __device__ __forceinline__ float fast_exp2(float x) { return __builtin_amdgcn_exp2f(x); }
; __device__ __forceinline__ float fast_rcp(float x) { return __builtin_amdgcn_rcpf(x); }
; __device__ __forceinline__ float siluf_(float x) { return x * sigmoidf_(x); }
; __device__ __forceinline__ v4u tr4(int a, v4u x) { return (v4u){bperm(a, x.x), bperm(a, x.y), bperm(a, x.z), bperm(a, x.w)}; }
; __device__ __forceinline__ v4u pack8(const f32x4& a, const f32x4& b) { return (v4u){pg8::cvt_pk_bf16(a[0], a[1]), pg8::cvt_pk_bf16(a[2], a[3]), pg8::cvt_pk_bf16(b[0], b[1]), pg8::cvt_pk_bf16(b[2], b[3])}; }
; __device__ __forceinline__ float sigmoidf_(float x) { return fast_rcp(1.0f + fast_exp2(-x * LOG2E)); }
;     __device__ __forceinline__ bool operator()(AccT& acc, const Unit& u, int wr, int wc, int fr, int fq) const {
;     ...
;         if (seg == 0 || seg == 1 || seg == 2 || seg >= 6) {
;             bf16* dst = (bf16*)(ws + (seg == 0 ? WS_VR : seg == 1 ? WS_GR : seg == 2 ? WS_QS : WS_GT)); const int ld = seg >= 6 ? 3 * D : D; const int cofs = seg >= 6 ? (seg - 6) * D : 0;
; #pragma unroll
;             for (int ai = 0; ai < 2; ++ai)
; #pragma unroll
;                 for (int m = 0; m < 4; ++m) { const size_t r = (size_t)(pm * 256 + trl0 + ai * 128 + m * 16);
; #pragma unroll
;                     for (int bj = 0; bj < 2; ++bj) { f32x4 v0 = acc[ai][bj][m][0], v1 = acc[ai][bj][m][1];
;                         if (seg == 1) {
; #pragma unroll
;                             for (int e = 0; e < 4; ++e) { v0[e] = siluf_(v0[e]); v1[e] = siluf_(v1[e]); } }
;                         else if (seg == 2) { v0 = v0 * (0.08838834764831845f * LOG2E); v1 = v1 * (0.08838834764831845f * LOG2E); }
;                         else if (seg >= 6) {
; #pragma unroll
;                             for (int e = 0; e < 4; ++e) { v0[e] = sigmoidf_(v0[e]); v1[e] = sigmoidf_(v1[e]); } }
;                         *(GAS v4u*)(dst + r * ld + cofs + colt + bj * 128) = tr4(t.pull, pack8(v0, v1)); } }
.LBB0_741:
	s_cmp_gt_u32 s31, 23
	s_cbranch_scc0 .Lwin_not_gates
	s_lshl_b32 s10, s29, 11
	s_add_i32 s10, s10, 0x5ecbd000
	s_waitcnt lgkmcnt(0)
	s_mov_b32 s100, 0xbfb8aa3b
	s_mov_b32 s101, 0xbfb8aa3b
	s_add_u32 s10, s46, s10
	s_addc_u32 s11, s47, 0
	v_lshl_add_u32 v142, s28, 8, v140
	v_ashrrev_i32_e32 v139, 31, v138
	v_lshl_add_u64 v[130:131], v[138:139], 1, s[10:11]
	s_movk_i32 s31, 0xc00
	v_mad_i64_i32 v[132:133], s[14:15], s31, v142, 0
	v_lshl_add_u64 v[184:185], v[132:133], 1, v[130:131]
	v_pk_mul_f32 v[162:163], v[126:127], s[100:101]
	v_pk_mul_f32 v[164:165], v[128:129], s[100:101]
	v_pk_mul_f32 v[166:167], v[122:123], s[100:101]
	v_pk_mul_f32 v[168:169], v[124:125], s[100:101]
	v_exp_f32_e32 v162, v162
	v_exp_f32_e32 v163, v163
	v_exp_f32_e32 v164, v164
	v_exp_f32_e32 v165, v165
	v_exp_f32_e32 v166, v166
	v_exp_f32_e32 v167, v167
	v_exp_f32_e32 v168, v168
	v_exp_f32_e32 v169, v169
	v_pk_add_f32 v[162:163], v[162:163], 1.0 op_sel_hi:[1,0]
	v_pk_add_f32 v[164:165], v[164:165], 1.0 op_sel_hi:[1,0]
	v_pk_add_f32 v[166:167], v[166:167], 1.0 op_sel_hi:[1,0]
	v_pk_add_f32 v[168:169], v[168:169], 1.0 op_sel_hi:[1,0]
	v_rcp_f32_e32 v162, v162
	v_rcp_f32_e32 v163, v163
	v_rcp_f32_e32 v164, v164
	v_rcp_f32_e32 v165, v165
	v_rcp_f32_e32 v166, v166
	v_rcp_f32_e32 v167, v167
	v_rcp_f32_e32 v168, v168
	v_rcp_f32_e32 v169, v169
	v_cvt_pk_bf16_f32 v170, v162, v163
	v_cvt_pk_bf16_f32 v171, v164, v165
	v_cvt_pk_bf16_f32 v172, v166, v167
	v_cvt_pk_bf16_f32 v173, v168, v169
	ds_bpermute_b32 v174, v157, v170
	ds_bpermute_b32 v175, v157, v171
	ds_bpermute_b32 v176, v157, v172
	ds_bpermute_b32 v177, v157, v173
	v_pk_mul_f32 v[162:163], v[118:119], s[100:101]
	v_pk_mul_f32 v[164:165], v[120:121], s[100:101]
	v_pk_mul_f32 v[166:167], v[114:115], s[100:101]
	v_pk_mul_f32 v[168:169], v[116:117], s[100:101]
	v_exp_f32_e32 v162, v162
	v_exp_f32_e32 v163, v163
	v_exp_f32_e32 v164, v164
	v_exp_f32_e32 v165, v165
	v_exp_f32_e32 v166, v166
	v_exp_f32_e32 v167, v167
	v_exp_f32_e32 v168, v168
	v_exp_f32_e32 v169, v169
	v_pk_add_f32 v[162:163], v[162:163], 1.0 op_sel_hi:[1,0]
	v_pk_add_f32 v[164:165], v[164:165], 1.0 op_sel_hi:[1,0]
	v_pk_add_f32 v[166:167], v[166:167], 1.0 op_sel_hi:[1,0]
	v_pk_add_f32 v[168:169], v[168:169], 1.0 op_sel_hi:[1,0]
	v_rcp_f32_e32 v162, v162
	v_rcp_f32_e32 v163, v163
	v_rcp_f32_e32 v164, v164
	v_rcp_f32_e32 v165, v165
	v_rcp_f32_e32 v166, v166
	v_rcp_f32_e32 v167, v167
	v_rcp_f32_e32 v168, v168
	v_rcp_f32_e32 v169, v169
	v_cvt_pk_bf16_f32 v170, v162, v163
	v_cvt_pk_bf16_f32 v171, v164, v165
	v_cvt_pk_bf16_f32 v172, v166, v167
	v_cvt_pk_bf16_f32 v173, v168, v169
	ds_bpermute_b32 v178, v157, v170
	ds_bpermute_b32 v179, v157, v171
	ds_bpermute_b32 v180, v157, v172
	ds_bpermute_b32 v181, v157, v173
	s_waitcnt lgkmcnt(4)
	global_store_dwordx4 v[184:185], v[174:177], off
	v_pk_mul_f32 v[162:163], v[110:111], s[100:101]
	v_pk_mul_f32 v[164:165], v[112:113], s[100:101]
	v_pk_mul_f32 v[166:167], v[106:107], s[100:101]
	v_pk_mul_f32 v[168:169], v[108:109], s[100:101]
	v_exp_f32_e32 v162, v162
	v_exp_f32_e32 v163, v163
	v_exp_f32_e32 v164, v164
	v_exp_f32_e32 v165, v165
	v_exp_f32_e32 v166, v166
	v_exp_f32_e32 v167, v167
	v_exp_f32_e32 v168, v168
	v_exp_f32_e32 v169, v169
	v_pk_add_f32 v[162:163], v[162:163], 1.0 op_sel_hi:[1,0]
	v_pk_add_f32 v[164:165], v[164:165], 1.0 op_sel_hi:[1,0]
	v_pk_add_f32 v[166:167], v[166:167], 1.0 op_sel_hi:[1,0]
	v_pk_add_f32 v[168:169], v[168:169], 1.0 op_sel_hi:[1,0]
	v_rcp_f32_e32 v162, v162
	v_rcp_f32_e32 v163, v163
	v_rcp_f32_e32 v164, v164
	v_rcp_f32_e32 v165, v165
	v_rcp_f32_e32 v166, v166
	v_rcp_f32_e32 v167, v167
	v_rcp_f32_e32 v168, v168
	v_rcp_f32_e32 v169, v169
	v_cvt_pk_bf16_f32 v170, v162, v163
	v_cvt_pk_bf16_f32 v171, v164, v165
	v_cvt_pk_bf16_f32 v172, v166, v167
	v_cvt_pk_bf16_f32 v173, v168, v169
	ds_bpermute_b32 v174, v157, v170
	ds_bpermute_b32 v175, v157, v171
	ds_bpermute_b32 v176, v157, v172
	ds_bpermute_b32 v177, v157, v173
	s_waitcnt lgkmcnt(4)
	global_store_dwordx4 v[184:185], v[178:181], off offset:256
	s_mov_b32 s10, 0x18000
	s_mov_b32 s11, 0
	v_lshl_add_u64 v[182:183], v[184:185], 0, s[10:11]
	v_pk_mul_f32 v[162:163], v[102:103], s[100:101]
	v_pk_mul_f32 v[164:165], v[104:105], s[100:101]
	v_pk_mul_f32 v[166:167], v[98:99], s[100:101]
	v_pk_mul_f32 v[168:169], v[100:101], s[100:101]
	v_exp_f32_e32 v162, v162
	v_exp_f32_e32 v163, v163
	v_exp_f32_e32 v164, v164
	v_exp_f32_e32 v165, v165
	v_exp_f32_e32 v166, v166
	v_exp_f32_e32 v167, v167
	v_exp_f32_e32 v168, v168
	v_exp_f32_e32 v169, v169
	v_pk_add_f32 v[162:163], v[162:163], 1.0 op_sel_hi:[1,0]
	v_pk_add_f32 v[164:165], v[164:165], 1.0 op_sel_hi:[1,0]
	v_pk_add_f32 v[166:167], v[166:167], 1.0 op_sel_hi:[1,0]
	v_pk_add_f32 v[168:169], v[168:169], 1.0 op_sel_hi:[1,0]
	v_rcp_f32_e32 v162, v162
	v_rcp_f32_e32 v163, v163
	v_rcp_f32_e32 v164, v164
	v_rcp_f32_e32 v165, v165
	v_rcp_f32_e32 v166, v166
	v_rcp_f32_e32 v167, v167
	v_rcp_f32_e32 v168, v168
	v_rcp_f32_e32 v169, v169
	v_cvt_pk_bf16_f32 v170, v162, v163
	v_cvt_pk_bf16_f32 v171, v164, v165
	v_cvt_pk_bf16_f32 v172, v166, v167
	v_cvt_pk_bf16_f32 v173, v168, v169
	ds_bpermute_b32 v178, v157, v170
	ds_bpermute_b32 v179, v157, v171
	ds_bpermute_b32 v180, v157, v172
	ds_bpermute_b32 v181, v157, v173
	s_waitcnt lgkmcnt(4)
; #define GAS __attribute__((address_space(1)))
; __device__ __forceinline__ float fast_exp2(float x) { return __builtin_amdgcn_exp2f(x); }
; __device__ __forceinline__ float fast_rcp(float x) { return __builtin_amdgcn_rcpf(x); }
; __device__ __forceinline__ float siluf_(float x) { return x * sigmoidf_(x); }
; __device__ __forceinline__ v4u tr4(int a, v4u x) { return (v4u){bperm(a, x.x), bperm(a, x.y), bperm(a, x.z), bperm(a, x.w)}; }
; __device__ __forceinline__ v4u pack8(const f32x4& a, const f32x4& b) { return (v4u){pg8::cvt_pk_bf16(a[0], a[1]), pg8::cvt_pk_bf16(a[2], a[3]), pg8::cvt_pk_bf16(b[0], b[1]), pg8::cvt_pk_bf16(b[2], b[3])}; }
; __device__ __forceinline__ float sigmoidf_(float x) { return fast_rcp(1.0f + fast_exp2(-x * LOG2E)); }
;     __device__ __forceinline__ bool operator()(AccT& acc, const Unit& u, int wr, int wc, int fr, int fq) const {
;     ...
;         if (seg == 0 || seg == 1 || seg == 2 || seg >= 6) {
;             bf16* dst = (bf16*)(ws + (seg == 0 ? WS_VR : seg == 1 ? WS_GR : seg == 2 ? WS_QS : WS_GT)); const int ld = seg >= 6 ? 3 * D : D; const int cofs = seg >= 6 ? (seg - 6) * D : 0;
; #pragma unroll
;             for (int ai = 0; ai < 2; ++ai)
; #pragma unroll
;                 for (int m = 0; m < 4; ++m) { const size_t r = (size_t)(pm * 256 + trl0 + ai * 128 + m * 16);
; #pragma unroll
;                     for (int bj = 0; bj < 2; ++bj) { f32x4 v0 = acc[ai][bj][m][0], v1 = acc[ai][bj][m][1];
;                         if (seg == 1) {
; #pragma unroll
;                             for (int e = 0; e < 4; ++e) { v0[e] = siluf_(v0[e]); v1[e] = siluf_(v1[e]); } }
;                         else if (seg == 2) { v0 = v0 * (0.08838834764831845f * LOG2E); v1 = v1 * (0.08838834764831845f * LOG2E); }
;                         else if (seg >= 6) {
; #pragma unroll
;                             for (int e = 0; e < 4; ++e) { v0[e] = sigmoidf_(v0[e]); v1[e] = sigmoidf_(v1[e]); } }
;                         *(GAS v4u*)(dst + r * ld + cofs + colt + bj * 128) = tr4(t.pull, pack8(v0, v1)); } }
	global_store_dwordx4 v[182:183], v[174:177], off
	v_pk_mul_f32 v[162:163], v[94:95], s[100:101]
	v_pk_mul_f32 v[164:165], v[96:97], s[100:101]
	v_pk_mul_f32 v[166:167], v[90:91], s[100:101]
	v_pk_mul_f32 v[168:169], v[92:93], s[100:101]
	v_exp_f32_e32 v162, v162
	v_exp_f32_e32 v163, v163
	v_exp_f32_e32 v164, v164
	v_exp_f32_e32 v165, v165
	v_exp_f32_e32 v166, v166
	v_exp_f32_e32 v167, v167
	v_exp_f32_e32 v168, v168
	v_exp_f32_e32 v169, v169
	v_pk_add_f32 v[162:163], v[162:163], 1.0 op_sel_hi:[1,0]
	v_pk_add_f32 v[164:165], v[164:165], 1.0 op_sel_hi:[1,0]
	v_pk_add_f32 v[166:167], v[166:167], 1.0 op_sel_hi:[1,0]
	v_pk_add_f32 v[168:169], v[168:169], 1.0 op_sel_hi:[1,0]
	v_rcp_f32_e32 v162, v162
	v_rcp_f32_e32 v163, v163
	v_rcp_f32_e32 v164, v164
	v_rcp_f32_e32 v165, v165
	v_rcp_f32_e32 v166, v166
	v_rcp_f32_e32 v167, v167
	v_rcp_f32_e32 v168, v168
	v_rcp_f32_e32 v169, v169
	v_cvt_pk_bf16_f32 v170, v162, v163
	v_cvt_pk_bf16_f32 v171, v164, v165
	v_cvt_pk_bf16_f32 v172, v166, v167
	v_cvt_pk_bf16_f32 v173, v168, v169
	ds_bpermute_b32 v174, v157, v170
	ds_bpermute_b32 v175, v157, v171
	ds_bpermute_b32 v176, v157, v172
	ds_bpermute_b32 v177, v157, v173
	s_waitcnt lgkmcnt(4)
	global_store_dwordx4 v[182:183], v[178:181], off offset:256
	s_mov_b32 s10, 0x30000
	s_mov_b32 s11, 0
	v_lshl_add_u64 v[182:183], v[184:185], 0, s[10:11]
	v_pk_mul_f32 v[162:163], v[86:87], s[100:101]
	v_pk_mul_f32 v[164:165], v[88:89], s[100:101]
	v_pk_mul_f32 v[166:167], v[82:83], s[100:101]
	v_pk_mul_f32 v[168:169], v[84:85], s[100:101]
	v_exp_f32_e32 v162, v162
	v_exp_f32_e32 v163, v163
	v_exp_f32_e32 v164, v164
	v_exp_f32_e32 v165, v165
	v_exp_f32_e32 v166, v166
	v_exp_f32_e32 v167, v167
	v_exp_f32_e32 v168, v168
	v_exp_f32_e32 v169, v169
	v_pk_add_f32 v[162:163], v[162:163], 1.0 op_sel_hi:[1,0]
	v_pk_add_f32 v[164:165], v[164:165], 1.0 op_sel_hi:[1,0]
	v_pk_add_f32 v[166:167], v[166:167], 1.0 op_sel_hi:[1,0]
	v_pk_add_f32 v[168:169], v[168:169], 1.0 op_sel_hi:[1,0]
	v_rcp_f32_e32 v162, v162
	v_rcp_f32_e32 v163, v163
	v_rcp_f32_e32 v164, v164
	v_rcp_f32_e32 v165, v165
	v_rcp_f32_e32 v166, v166
	v_rcp_f32_e32 v167, v167
	v_rcp_f32_e32 v168, v168
	v_rcp_f32_e32 v169, v169
	v_cvt_pk_bf16_f32 v170, v162, v163
	v_cvt_pk_bf16_f32 v171, v164, v165
	v_cvt_pk_bf16_f32 v172, v166, v167
	v_cvt_pk_bf16_f32 v173, v168, v169
	ds_bpermute_b32 v178, v157, v170
	ds_bpermute_b32 v179, v157, v171
	ds_bpermute_b32 v180, v157, v172
	ds_bpermute_b32 v181, v157, v173
	s_waitcnt lgkmcnt(4)
	global_store_dwordx4 v[182:183], v[174:177], off
	v_pk_mul_f32 v[162:163], v[78:79], s[100:101]
	v_pk_mul_f32 v[164:165], v[80:81], s[100:101]
	v_pk_mul_f32 v[166:167], v[74:75], s[100:101]
	v_pk_mul_f32 v[168:169], v[76:77], s[100:101]
	v_exp_f32_e32 v162, v162
	v_exp_f32_e32 v163, v163
	v_exp_f32_e32 v164, v164
	v_exp_f32_e32 v165, v165
	v_exp_f32_e32 v166, v166
	v_exp_f32_e32 v167, v167
	v_exp_f32_e32 v168, v168
	v_exp_f32_e32 v169, v169
	v_pk_add_f32 v[162:163], v[162:163], 1.0 op_sel_hi:[1,0]
	v_pk_add_f32 v[164:165], v[164:165], 1.0 op_sel_hi:[1,0]
	v_pk_add_f32 v[166:167], v[166:167], 1.0 op_sel_hi:[1,0]
	v_pk_add_f32 v[168:169], v[168:169], 1.0 op_sel_hi:[1,0]
	v_rcp_f32_e32 v162, v162
	v_rcp_f32_e32 v163, v163
	v_rcp_f32_e32 v164, v164
	v_rcp_f32_e32 v165, v165
	v_rcp_f32_e32 v166, v166
	v_rcp_f32_e32 v167, v167
	v_rcp_f32_e32 v168, v168
	v_rcp_f32_e32 v169, v169
	v_cvt_pk_bf16_f32 v170, v162, v163
	v_cvt_pk_bf16_f32 v171, v164, v165
	v_cvt_pk_bf16_f32 v172, v166, v167
	v_cvt_pk_bf16_f32 v173, v168, v169
	ds_bpermute_b32 v174, v157, v170
	ds_bpermute_b32 v175, v157, v171
	ds_bpermute_b32 v176, v157, v172
	ds_bpermute_b32 v177, v157, v173
	s_waitcnt lgkmcnt(4)
	global_store_dwordx4 v[182:183], v[178:181], off offset:256
	s_mov_b32 s10, 0x48000
	s_mov_b32 s11, 0
	v_lshl_add_u64 v[182:183], v[184:185], 0, s[10:11]
	v_pk_mul_f32 v[162:163], v[70:71], s[100:101]
	v_pk_mul_f32 v[164:165], v[72:73], s[100:101]
	v_pk_mul_f32 v[166:167], v[66:67], s[100:101]
	v_pk_mul_f32 v[168:169], v[68:69], s[100:101]
	v_exp_f32_e32 v162, v162
	v_exp_f32_e32 v163, v163
	v_exp_f32_e32 v164, v164
	v_exp_f32_e32 v165, v165
	v_exp_f32_e32 v166, v166
	v_exp_f32_e32 v167, v167
	v_exp_f32_e32 v168, v168
	v_exp_f32_e32 v169, v169
	v_pk_add_f32 v[162:163], v[162:163], 1.0 op_sel_hi:[1,0]
	v_pk_add_f32 v[164:165], v[164:165], 1.0 op_sel_hi:[1,0]
	v_pk_add_f32 v[166:167], v[166:167], 1.0 op_sel_hi:[1,0]
	v_pk_add_f32 v[168:169], v[168:169], 1.0 op_sel_hi:[1,0]
	v_rcp_f32_e32 v162, v162
	v_rcp_f32_e32 v163, v163
	v_rcp_f32_e32 v164, v164
	v_rcp_f32_e32 v165, v165
	v_rcp_f32_e32 v166, v166
	v_rcp_f32_e32 v167, v167
	v_rcp_f32_e32 v168, v168
	v_rcp_f32_e32 v169, v169
	v_cvt_pk_bf16_f32 v170, v162, v163
	v_cvt_pk_bf16_f32 v171, v164, v165
	v_cvt_pk_bf16_f32 v172, v166, v167
	v_cvt_pk_bf16_f32 v173, v168, v169
	ds_bpermute_b32 v178, v157, v170
	ds_bpermute_b32 v179, v157, v171
	ds_bpermute_b32 v180, v157, v172
	ds_bpermute_b32 v181, v157, v173
	s_waitcnt lgkmcnt(4)
	global_store_dwordx4 v[182:183], v[174:177], off
	v_pk_mul_f32 v[162:163], v[62:63], s[100:101]
	v_pk_mul_f32 v[164:165], v[64:65], s[100:101]
	v_pk_mul_f32 v[166:167], v[58:59], s[100:101]
	v_pk_mul_f32 v[168:169], v[60:61], s[100:101]
	v_exp_f32_e32 v162, v162
	v_exp_f32_e32 v163, v163
	v_exp_f32_e32 v164, v164
	v_exp_f32_e32 v165, v165
	v_exp_f32_e32 v166, v166
	v_exp_f32_e32 v167, v167
	v_exp_f32_e32 v168, v168
	v_exp_f32_e32 v169, v169
	v_pk_add_f32 v[162:163], v[162:163], 1.0 op_sel_hi:[1,0]
	v_pk_add_f32 v[164:165], v[164:165], 1.0 op_sel_hi:[1,0]
	v_pk_add_f32 v[166:167], v[166:167], 1.0 op_sel_hi:[1,0]
	v_pk_add_f32 v[168:169], v[168:169], 1.0 op_sel_hi:[1,0]
	v_rcp_f32_e32 v162, v162
	v_rcp_f32_e32 v163, v163
	v_rcp_f32_e32 v164, v164
	v_rcp_f32_e32 v165, v165
	v_rcp_f32_e32 v166, v166
	v_rcp_f32_e32 v167, v167
	v_rcp_f32_e32 v168, v168
	v_rcp_f32_e32 v169, v169
	v_cvt_pk_bf16_f32 v170, v162, v163
	v_cvt_pk_bf16_f32 v171, v164, v165
	v_cvt_pk_bf16_f32 v172, v166, v167
	v_cvt_pk_bf16_f32 v173, v168, v169
	ds_bpermute_b32 v174, v157, v170
	ds_bpermute_b32 v175, v157, v171
	ds_bpermute_b32 v176, v157, v172
	ds_bpermute_b32 v177, v157, v173
	s_waitcnt lgkmcnt(4)
; #define GAS __attribute__((address_space(1)))
; __device__ __forceinline__ float fast_exp2(float x) { return __builtin_amdgcn_exp2f(x); }
; __device__ __forceinline__ float fast_rcp(float x) { return __builtin_amdgcn_rcpf(x); }
; __device__ __forceinline__ float siluf_(float x) { return x * sigmoidf_(x); }
; __device__ __forceinline__ v4u tr4(int a, v4u x) { return (v4u){bperm(a, x.x), bperm(a, x.y), bperm(a, x.z), bperm(a, x.w)}; }
; __device__ __forceinline__ v4u pack8(const f32x4& a, const f32x4& b) { return (v4u){pg8::cvt_pk_bf16(a[0], a[1]), pg8::cvt_pk_bf16(a[2], a[3]), pg8::cvt_pk_bf16(b[0], b[1]), pg8::cvt_pk_bf16(b[2], b[3])}; }
; __device__ __forceinline__ float sigmoidf_(float x) { return fast_rcp(1.0f + fast_exp2(-x * LOG2E)); }
;     __device__ __forceinline__ bool operator()(AccT& acc, const Unit& u, int wr, int wc, int fr, int fq) const {
;     ...
;         if (seg == 0 || seg == 1 || seg == 2 || seg >= 6) {
;             bf16* dst = (bf16*)(ws + (seg == 0 ? WS_VR : seg == 1 ? WS_GR : seg == 2 ? WS_QS : WS_GT)); const int ld = seg >= 6 ? 3 * D : D; const int cofs = seg >= 6 ? (seg - 6) * D : 0;
; #pragma unroll
;             for (int ai = 0; ai < 2; ++ai)
; #pragma unroll
;                 for (int m = 0; m < 4; ++m) { const size_t r = (size_t)(pm * 256 + trl0 + ai * 128 + m * 16);
; #pragma unroll
;                     for (int bj = 0; bj < 2; ++bj) { f32x4 v0 = acc[ai][bj][m][0], v1 = acc[ai][bj][m][1];
;                         if (seg == 1) {
; #pragma unroll
;                             for (int e = 0; e < 4; ++e) { v0[e] = siluf_(v0[e]); v1[e] = siluf_(v1[e]); } }
;                         else if (seg == 2) { v0 = v0 * (0.08838834764831845f * LOG2E); v1 = v1 * (0.08838834764831845f * LOG2E); }
;                         else if (seg >= 6) {
; #pragma unroll
;                             for (int e = 0; e < 4; ++e) { v0[e] = sigmoidf_(v0[e]); v1[e] = sigmoidf_(v1[e]); } }
;                         *(GAS v4u*)(dst + r * ld + cofs + colt + bj * 128) = tr4(t.pull, pack8(v0, v1)); } }
	global_store_dwordx4 v[182:183], v[178:181], off offset:256
	s_mov_b32 s10, 0xc0000
	s_mov_b32 s11, 0
	v_lshl_add_u64 v[182:183], v[184:185], 0, s[10:11]
	v_pk_mul_f32 v[162:163], v[54:55], s[100:101]
	v_pk_mul_f32 v[164:165], v[56:57], s[100:101]
	v_pk_mul_f32 v[166:167], v[50:51], s[100:101]
	v_pk_mul_f32 v[168:169], v[52:53], s[100:101]
	v_exp_f32_e32 v162, v162
	v_exp_f32_e32 v163, v163
	v_exp_f32_e32 v164, v164
	v_exp_f32_e32 v165, v165
	v_exp_f32_e32 v166, v166
	v_exp_f32_e32 v167, v167
	v_exp_f32_e32 v168, v168
	v_exp_f32_e32 v169, v169
	v_pk_add_f32 v[162:163], v[162:163], 1.0 op_sel_hi:[1,0]
	v_pk_add_f32 v[164:165], v[164:165], 1.0 op_sel_hi:[1,0]
	v_pk_add_f32 v[166:167], v[166:167], 1.0 op_sel_hi:[1,0]
	v_pk_add_f32 v[168:169], v[168:169], 1.0 op_sel_hi:[1,0]
	v_rcp_f32_e32 v162, v162
	v_rcp_f32_e32 v163, v163
	v_rcp_f32_e32 v164, v164
	v_rcp_f32_e32 v165, v165
	v_rcp_f32_e32 v166, v166
	v_rcp_f32_e32 v167, v167
	v_rcp_f32_e32 v168, v168
	v_rcp_f32_e32 v169, v169
	v_cvt_pk_bf16_f32 v170, v162, v163
	v_cvt_pk_bf16_f32 v171, v164, v165
	v_cvt_pk_bf16_f32 v172, v166, v167
	v_cvt_pk_bf16_f32 v173, v168, v169
	ds_bpermute_b32 v178, v157, v170
	ds_bpermute_b32 v179, v157, v171
	ds_bpermute_b32 v180, v157, v172
	ds_bpermute_b32 v181, v157, v173
	s_waitcnt lgkmcnt(4)
	global_store_dwordx4 v[182:183], v[174:177], off
	v_pk_mul_f32 v[162:163], v[46:47], s[100:101]
	v_pk_mul_f32 v[164:165], v[48:49], s[100:101]
	v_pk_mul_f32 v[166:167], v[42:43], s[100:101]
	v_pk_mul_f32 v[168:169], v[44:45], s[100:101]
	v_exp_f32_e32 v162, v162
	v_exp_f32_e32 v163, v163
	v_exp_f32_e32 v164, v164
	v_exp_f32_e32 v165, v165
	v_exp_f32_e32 v166, v166
	v_exp_f32_e32 v167, v167
	v_exp_f32_e32 v168, v168
	v_exp_f32_e32 v169, v169
	v_pk_add_f32 v[162:163], v[162:163], 1.0 op_sel_hi:[1,0]
	v_pk_add_f32 v[164:165], v[164:165], 1.0 op_sel_hi:[1,0]
	v_pk_add_f32 v[166:167], v[166:167], 1.0 op_sel_hi:[1,0]
	v_pk_add_f32 v[168:169], v[168:169], 1.0 op_sel_hi:[1,0]
	v_rcp_f32_e32 v162, v162
	v_rcp_f32_e32 v163, v163
	v_rcp_f32_e32 v164, v164
	v_rcp_f32_e32 v165, v165
	v_rcp_f32_e32 v166, v166
	v_rcp_f32_e32 v167, v167
	v_rcp_f32_e32 v168, v168
	v_rcp_f32_e32 v169, v169
	v_cvt_pk_bf16_f32 v170, v162, v163
	v_cvt_pk_bf16_f32 v171, v164, v165
	v_cvt_pk_bf16_f32 v172, v166, v167
	v_cvt_pk_bf16_f32 v173, v168, v169
	ds_bpermute_b32 v174, v157, v170
	ds_bpermute_b32 v175, v157, v171
	ds_bpermute_b32 v176, v157, v172
	ds_bpermute_b32 v177, v157, v173
	s_waitcnt lgkmcnt(4)
	global_store_dwordx4 v[182:183], v[178:181], off offset:256
	s_mov_b32 s10, 0xd8000
	s_mov_b32 s11, 0
	v_lshl_add_u64 v[182:183], v[184:185], 0, s[10:11]
	v_pk_mul_f32 v[162:163], v[38:39], s[100:101]
	v_pk_mul_f32 v[164:165], v[40:41], s[100:101]
	v_pk_mul_f32 v[166:167], v[34:35], s[100:101]
	v_pk_mul_f32 v[168:169], v[36:37], s[100:101]
	v_exp_f32_e32 v162, v162
	v_exp_f32_e32 v163, v163
	v_exp_f32_e32 v164, v164
	v_exp_f32_e32 v165, v165
	v_exp_f32_e32 v166, v166
	v_exp_f32_e32 v167, v167
	v_exp_f32_e32 v168, v168
	v_exp_f32_e32 v169, v169
	v_pk_add_f32 v[162:163], v[162:163], 1.0 op_sel_hi:[1,0]
	v_pk_add_f32 v[164:165], v[164:165], 1.0 op_sel_hi:[1,0]
	v_pk_add_f32 v[166:167], v[166:167], 1.0 op_sel_hi:[1,0]
	v_pk_add_f32 v[168:169], v[168:169], 1.0 op_sel_hi:[1,0]
	v_rcp_f32_e32 v162, v162
	v_rcp_f32_e32 v163, v163
	v_rcp_f32_e32 v164, v164
	v_rcp_f32_e32 v165, v165
	v_rcp_f32_e32 v166, v166
	v_rcp_f32_e32 v167, v167
	v_rcp_f32_e32 v168, v168
	v_rcp_f32_e32 v169, v169
	v_cvt_pk_bf16_f32 v170, v162, v163
	v_cvt_pk_bf16_f32 v171, v164, v165
	v_cvt_pk_bf16_f32 v172, v166, v167
	v_cvt_pk_bf16_f32 v173, v168, v169
	ds_bpermute_b32 v178, v157, v170
	ds_bpermute_b32 v179, v157, v171
	ds_bpermute_b32 v180, v157, v172
	ds_bpermute_b32 v181, v157, v173
	s_waitcnt lgkmcnt(4)
	global_store_dwordx4 v[182:183], v[174:177], off
	v_pk_mul_f32 v[162:163], v[30:31], s[100:101]
	v_pk_mul_f32 v[164:165], v[32:33], s[100:101]
	v_pk_mul_f32 v[166:167], v[26:27], s[100:101]
	v_pk_mul_f32 v[168:169], v[28:29], s[100:101]
	v_exp_f32_e32 v162, v162
	v_exp_f32_e32 v163, v163
	v_exp_f32_e32 v164, v164
	v_exp_f32_e32 v165, v165
	v_exp_f32_e32 v166, v166
	v_exp_f32_e32 v167, v167
	v_exp_f32_e32 v168, v168
	v_exp_f32_e32 v169, v169
	v_pk_add_f32 v[162:163], v[162:163], 1.0 op_sel_hi:[1,0]
	v_pk_add_f32 v[164:165], v[164:165], 1.0 op_sel_hi:[1,0]
	v_pk_add_f32 v[166:167], v[166:167], 1.0 op_sel_hi:[1,0]
	v_pk_add_f32 v[168:169], v[168:169], 1.0 op_sel_hi:[1,0]
	v_rcp_f32_e32 v162, v162
	v_rcp_f32_e32 v163, v163
	v_rcp_f32_e32 v164, v164
	v_rcp_f32_e32 v165, v165
	v_rcp_f32_e32 v166, v166
	v_rcp_f32_e32 v167, v167
	v_rcp_f32_e32 v168, v168
	v_rcp_f32_e32 v169, v169
	v_cvt_pk_bf16_f32 v170, v162, v163
	v_cvt_pk_bf16_f32 v171, v164, v165
	v_cvt_pk_bf16_f32 v172, v166, v167
	v_cvt_pk_bf16_f32 v173, v168, v169
	ds_bpermute_b32 v174, v157, v170
	ds_bpermute_b32 v175, v157, v171
	ds_bpermute_b32 v176, v157, v172
	ds_bpermute_b32 v177, v157, v173
	s_waitcnt lgkmcnt(4)
	global_store_dwordx4 v[182:183], v[178:181], off offset:256
	s_mov_b32 s10, 0xf0000
	s_mov_b32 s11, 0
	v_lshl_add_u64 v[182:183], v[184:185], 0, s[10:11]
	v_pk_mul_f32 v[162:163], v[22:23], s[100:101]
	v_pk_mul_f32 v[164:165], v[24:25], s[100:101]
	v_pk_mul_f32 v[166:167], v[18:19], s[100:101]
	v_pk_mul_f32 v[168:169], v[20:21], s[100:101]
	v_exp_f32_e32 v162, v162
	v_exp_f32_e32 v163, v163
	v_exp_f32_e32 v164, v164
	v_exp_f32_e32 v165, v165
	v_exp_f32_e32 v166, v166
	v_exp_f32_e32 v167, v167
	v_exp_f32_e32 v168, v168
	v_exp_f32_e32 v169, v169
	v_pk_add_f32 v[162:163], v[162:163], 1.0 op_sel_hi:[1,0]
	v_pk_add_f32 v[164:165], v[164:165], 1.0 op_sel_hi:[1,0]
	v_pk_add_f32 v[166:167], v[166:167], 1.0 op_sel_hi:[1,0]
	v_pk_add_f32 v[168:169], v[168:169], 1.0 op_sel_hi:[1,0]
	v_rcp_f32_e32 v162, v162
	v_rcp_f32_e32 v163, v163
	v_rcp_f32_e32 v164, v164
	v_rcp_f32_e32 v165, v165
	v_rcp_f32_e32 v166, v166
	v_rcp_f32_e32 v167, v167
	v_rcp_f32_e32 v168, v168
	v_rcp_f32_e32 v169, v169
	v_cvt_pk_bf16_f32 v170, v162, v163
	v_cvt_pk_bf16_f32 v171, v164, v165
	v_cvt_pk_bf16_f32 v172, v166, v167
	v_cvt_pk_bf16_f32 v173, v168, v169
	ds_bpermute_b32 v178, v157, v170
	ds_bpermute_b32 v179, v157, v171
	ds_bpermute_b32 v180, v157, v172
	ds_bpermute_b32 v181, v157, v173
	s_waitcnt lgkmcnt(4)
; #define GAS __attribute__((address_space(1)))
; __device__ __forceinline__ float fast_exp2(float x) { return __builtin_amdgcn_exp2f(x); }
; __device__ __forceinline__ float fast_rcp(float x) { return __builtin_amdgcn_rcpf(x); }
; __device__ __forceinline__ v4u tr4(int a, v4u x) { return (v4u){bperm(a, x.x), bperm(a, x.y), bperm(a, x.z), bperm(a, x.w)}; }
; __device__ __forceinline__ v4u pack8(const f32x4& a, const f32x4& b) { return (v4u){pg8::cvt_pk_bf16(a[0], a[1]), pg8::cvt_pk_bf16(a[2], a[3]), pg8::cvt_pk_bf16(b[0], b[1]), pg8::cvt_pk_bf16(b[2], b[3])}; }
; __device__ __forceinline__ float sigmoidf_(float x) { return fast_rcp(1.0f + fast_exp2(-x * LOG2E)); }
; __device__ __forceinline__ float siluf_(float x) { return x * sigmoidf_(x); }
;     __device__ __forceinline__ bool operator()(AccT& acc, const Unit& u, int wr, int wc, int fr, int fq) const {
;     ...
;         if (seg == 0 || seg == 1 || seg == 2 || seg >= 6) {
;             bf16* dst = (bf16*)(ws + (seg == 0 ? WS_VR : seg == 1 ? WS_GR : seg == 2 ? WS_QS : WS_GT)); const int ld = seg >= 6 ? 3 * D : D; const int cofs = seg >= 6 ? (seg - 6) * D : 0;
; #pragma unroll
;             for (int ai = 0; ai < 2; ++ai)
; #pragma unroll
;                 for (int m = 0; m < 4; ++m) { const size_t r = (size_t)(pm * 256 + trl0 + ai * 128 + m * 16);
; #pragma unroll
;                     for (int bj = 0; bj < 2; ++bj) { f32x4 v0 = acc[ai][bj][m][0], v1 = acc[ai][bj][m][1];
;                         if (seg == 1) {
; #pragma unroll
;                             for (int e = 0; e < 4; ++e) { v0[e] = siluf_(v0[e]); v1[e] = siluf_(v1[e]); } }
;                         else if (seg == 2) { v0 = v0 * (0.08838834764831845f * LOG2E); v1 = v1 * (0.08838834764831845f * LOG2E); }
;                         else if (seg >= 6) {
; #pragma unroll
;                             for (int e = 0; e < 4; ++e) { v0[e] = sigmoidf_(v0[e]); v1[e] = sigmoidf_(v1[e]); } }
;                         *(GAS v4u*)(dst + r * ld + cofs + colt + bj * 128) = tr4(t.pull, pack8(v0, v1)); } }
	global_store_dwordx4 v[182:183], v[174:177], off
	v_pk_mul_f32 v[162:163], v[14:15], s[100:101]
	v_pk_mul_f32 v[164:165], v[16:17], s[100:101]
	v_pk_mul_f32 v[166:167], v[10:11], s[100:101]
	v_pk_mul_f32 v[168:169], v[12:13], s[100:101]
	v_exp_f32_e32 v162, v162
	v_exp_f32_e32 v163, v163
	v_exp_f32_e32 v164, v164
	v_exp_f32_e32 v165, v165
	v_exp_f32_e32 v166, v166
	v_exp_f32_e32 v167, v167
	v_exp_f32_e32 v168, v168
	v_exp_f32_e32 v169, v169
	v_pk_add_f32 v[162:163], v[162:163], 1.0 op_sel_hi:[1,0]
	v_pk_add_f32 v[164:165], v[164:165], 1.0 op_sel_hi:[1,0]
	v_pk_add_f32 v[166:167], v[166:167], 1.0 op_sel_hi:[1,0]
	v_pk_add_f32 v[168:169], v[168:169], 1.0 op_sel_hi:[1,0]
	v_rcp_f32_e32 v162, v162
	v_rcp_f32_e32 v163, v163
	v_rcp_f32_e32 v164, v164
	v_rcp_f32_e32 v165, v165
	v_rcp_f32_e32 v166, v166
	v_rcp_f32_e32 v167, v167
	v_rcp_f32_e32 v168, v168
	v_rcp_f32_e32 v169, v169
	v_cvt_pk_bf16_f32 v170, v162, v163
	v_cvt_pk_bf16_f32 v171, v164, v165
	v_cvt_pk_bf16_f32 v172, v166, v167
	v_cvt_pk_bf16_f32 v173, v168, v169
	ds_bpermute_b32 v174, v157, v170
	ds_bpermute_b32 v175, v157, v171
	ds_bpermute_b32 v176, v157, v172
	ds_bpermute_b32 v177, v157, v173
	s_waitcnt lgkmcnt(4)
	global_store_dwordx4 v[182:183], v[178:181], off offset:256
	s_mov_b32 s10, 0x108000
	s_mov_b32 s11, 0
	v_lshl_add_u64 v[182:183], v[184:185], 0, s[10:11]
	v_pk_mul_f32 v[162:163], v[6:7], s[100:101]
	v_pk_mul_f32 v[164:165], v[8:9], s[100:101]
	v_pk_mul_f32 v[166:167], v[2:3], s[100:101]
	v_pk_mul_f32 v[168:169], v[4:5], s[100:101]
	v_exp_f32_e32 v162, v162
	v_exp_f32_e32 v163, v163
	v_exp_f32_e32 v164, v164
	v_exp_f32_e32 v165, v165
	v_exp_f32_e32 v166, v166
	v_exp_f32_e32 v167, v167
	v_exp_f32_e32 v168, v168
	v_exp_f32_e32 v169, v169
	v_pk_add_f32 v[162:163], v[162:163], 1.0 op_sel_hi:[1,0]
	v_pk_add_f32 v[164:165], v[164:165], 1.0 op_sel_hi:[1,0]
	v_pk_add_f32 v[166:167], v[166:167], 1.0 op_sel_hi:[1,0]
	v_pk_add_f32 v[168:169], v[168:169], 1.0 op_sel_hi:[1,0]
	v_rcp_f32_e32 v162, v162
	v_rcp_f32_e32 v163, v163
	v_rcp_f32_e32 v164, v164
	v_rcp_f32_e32 v165, v165
	v_rcp_f32_e32 v166, v166
	v_rcp_f32_e32 v167, v167
	v_rcp_f32_e32 v168, v168
	v_rcp_f32_e32 v169, v169
	v_cvt_pk_bf16_f32 v170, v162, v163
	v_cvt_pk_bf16_f32 v171, v164, v165
	v_cvt_pk_bf16_f32 v172, v166, v167
	v_cvt_pk_bf16_f32 v173, v168, v169
	ds_bpermute_b32 v178, v157, v170
	ds_bpermute_b32 v179, v157, v171
	ds_bpermute_b32 v180, v157, v172
	ds_bpermute_b32 v181, v157, v173
	s_waitcnt lgkmcnt(4)
	global_store_dwordx4 v[182:183], v[174:177], off
	s_waitcnt lgkmcnt(0)
	global_store_dwordx4 v[182:183], v[178:181], off offset:256
	s_mov_b64 s[12:13], 0
	s_branch .LBB0_902
.Lwin_not_gates:
	s_cmp_eq_u32 s29, 1
	s_cbranch_scc0 .Lwin_not_silu
	s_mov_b32 s10, 0x367c0000
	s_waitcnt lgkmcnt(0)
	s_mov_b32 s100, 0xbfb8aa3b
	s_mov_b32 s101, 0xbfb8aa3b
	s_add_u32 s10, s46, s10
	s_addc_u32 s11, s47, 0
	v_lshl_add_u32 v142, s28, 8, v140
	v_ashrrev_i32_e32 v139, 31, v138
	v_lshl_add_u64 v[130:131], v[138:139], 1, s[10:11]
	s_movk_i32 s31, 0x400
	v_mad_i64_i32 v[132:133], s[14:15], s31, v142, 0
	v_lshl_add_u64 v[184:185], v[132:133], 1, v[130:131]
	v_pk_mul_f32 v[162:163], v[126:127], s[100:101]
	v_pk_mul_f32 v[164:165], v[128:129], s[100:101]
	v_pk_mul_f32 v[166:167], v[122:123], s[100:101]
	v_pk_mul_f32 v[168:169], v[124:125], s[100:101]
	v_exp_f32_e32 v162, v162
	v_exp_f32_e32 v163, v163
	v_exp_f32_e32 v164, v164
	v_exp_f32_e32 v165, v165
	v_exp_f32_e32 v166, v166
	v_exp_f32_e32 v167, v167
	v_exp_f32_e32 v168, v168
	v_exp_f32_e32 v169, v169
	v_pk_add_f32 v[162:163], v[162:163], 1.0 op_sel_hi:[1,0]
	v_pk_add_f32 v[164:165], v[164:165], 1.0 op_sel_hi:[1,0]
	v_pk_add_f32 v[166:167], v[166:167], 1.0 op_sel_hi:[1,0]
	v_pk_add_f32 v[168:169], v[168:169], 1.0 op_sel_hi:[1,0]
	v_rcp_f32_e32 v162, v162
	v_rcp_f32_e32 v163, v163
	v_rcp_f32_e32 v164, v164
	v_rcp_f32_e32 v165, v165
	v_rcp_f32_e32 v166, v166
	v_rcp_f32_e32 v167, v167
	v_rcp_f32_e32 v168, v168
	v_rcp_f32_e32 v169, v169
	v_pk_mul_f32 v[162:163], v[126:127], v[162:163]
	v_pk_mul_f32 v[164:165], v[128:129], v[164:165]
	v_pk_mul_f32 v[166:167], v[122:123], v[166:167]
	v_pk_mul_f32 v[168:169], v[124:125], v[168:169]
	v_cvt_pk_bf16_f32 v170, v162, v163
	v_cvt_pk_bf16_f32 v171, v164, v165
	v_cvt_pk_bf16_f32 v172, v166, v167
	v_cvt_pk_bf16_f32 v173, v168, v169
	ds_bpermute_b32 v174, v157, v170
	ds_bpermute_b32 v175, v157, v171
	ds_bpermute_b32 v176, v157, v172
	ds_bpermute_b32 v177, v157, v173
	v_pk_mul_f32 v[162:163], v[118:119], s[100:101]
	v_pk_mul_f32 v[164:165], v[120:121], s[100:101]
	v_pk_mul_f32 v[166:167], v[114:115], s[100:101]
	v_pk_mul_f32 v[168:169], v[116:117], s[100:101]
	v_exp_f32_e32 v162, v162
	v_exp_f32_e32 v163, v163
	v_exp_f32_e32 v164, v164
	v_exp_f32_e32 v165, v165
	v_exp_f32_e32 v166, v166
	v_exp_f32_e32 v167, v167
	v_exp_f32_e32 v168, v168
	v_exp_f32_e32 v169, v169
	v_pk_add_f32 v[162:163], v[162:163], 1.0 op_sel_hi:[1,0]
	v_pk_add_f32 v[164:165], v[164:165], 1.0 op_sel_hi:[1,0]
	v_pk_add_f32 v[166:167], v[166:167], 1.0 op_sel_hi:[1,0]
	v_pk_add_f32 v[168:169], v[168:169], 1.0 op_sel_hi:[1,0]
	v_rcp_f32_e32 v162, v162
	v_rcp_f32_e32 v163, v163
	v_rcp_f32_e32 v164, v164
	v_rcp_f32_e32 v165, v165
	v_rcp_f32_e32 v166, v166
	v_rcp_f32_e32 v167, v167
	v_rcp_f32_e32 v168, v168
	v_rcp_f32_e32 v169, v169
	v_pk_mul_f32 v[162:163], v[118:119], v[162:163]
	v_pk_mul_f32 v[164:165], v[120:121], v[164:165]
	v_pk_mul_f32 v[166:167], v[114:115], v[166:167]
	v_pk_mul_f32 v[168:169], v[116:117], v[168:169]
	v_cvt_pk_bf16_f32 v170, v162, v163
	v_cvt_pk_bf16_f32 v171, v164, v165
	v_cvt_pk_bf16_f32 v172, v166, v167
	v_cvt_pk_bf16_f32 v173, v168, v169
	ds_bpermute_b32 v178, v157, v170
	ds_bpermute_b32 v179, v157, v171
	ds_bpermute_b32 v180, v157, v172
	ds_bpermute_b32 v181, v157, v173
	s_waitcnt lgkmcnt(4)
; #define GAS __attribute__((address_space(1)))
; __device__ __forceinline__ float fast_exp2(float x) { return __builtin_amdgcn_exp2f(x); }
; __device__ __forceinline__ float fast_rcp(float x) { return __builtin_amdgcn_rcpf(x); }
; __device__ __forceinline__ v4u tr4(int a, v4u x) { return (v4u){bperm(a, x.x), bperm(a, x.y), bperm(a, x.z), bperm(a, x.w)}; }
; __device__ __forceinline__ v4u pack8(const f32x4& a, const f32x4& b) { return (v4u){pg8::cvt_pk_bf16(a[0], a[1]), pg8::cvt_pk_bf16(a[2], a[3]), pg8::cvt_pk_bf16(b[0], b[1]), pg8::cvt_pk_bf16(b[2], b[3])}; }
; __device__ __forceinline__ float sigmoidf_(float x) { return fast_rcp(1.0f + fast_exp2(-x * LOG2E)); }
; __device__ __forceinline__ float siluf_(float x) { return x * sigmoidf_(x); }
;     __device__ __forceinline__ bool operator()(AccT& acc, const Unit& u, int wr, int wc, int fr, int fq) const {
;     ...
;         if (seg == 0 || seg == 1 || seg == 2 || seg >= 6) {
;             bf16* dst = (bf16*)(ws + (seg == 0 ? WS_VR : seg == 1 ? WS_GR : seg == 2 ? WS_QS : WS_GT)); const int ld = seg >= 6 ? 3 * D : D; const int cofs = seg >= 6 ? (seg - 6) * D : 0;
; #pragma unroll
;             for (int ai = 0; ai < 2; ++ai)
; #pragma unroll
;                 for (int m = 0; m < 4; ++m) { const size_t r = (size_t)(pm * 256 + trl0 + ai * 128 + m * 16);
; #pragma unroll
;                     for (int bj = 0; bj < 2; ++bj) { f32x4 v0 = acc[ai][bj][m][0], v1 = acc[ai][bj][m][1];
;                         if (seg == 1) {
; #pragma unroll
;                             for (int e = 0; e < 4; ++e) { v0[e] = siluf_(v0[e]); v1[e] = siluf_(v1[e]); } }
;                         else if (seg == 2) { v0 = v0 * (0.08838834764831845f * LOG2E); v1 = v1 * (0.08838834764831845f * LOG2E); }
;                         else if (seg >= 6) {
; #pragma unroll
;                             for (int e = 0; e < 4; ++e) { v0[e] = sigmoidf_(v0[e]); v1[e] = sigmoidf_(v1[e]); } }
;                         *(GAS v4u*)(dst + r * ld + cofs + colt + bj * 128) = tr4(t.pull, pack8(v0, v1)); } }
	global_store_dwordx4 v[184:185], v[174:177], off
	v_pk_mul_f32 v[162:163], v[110:111], s[100:101]
	v_pk_mul_f32 v[164:165], v[112:113], s[100:101]
	v_pk_mul_f32 v[166:167], v[106:107], s[100:101]
	v_pk_mul_f32 v[168:169], v[108:109], s[100:101]
	v_exp_f32_e32 v162, v162
	v_exp_f32_e32 v163, v163
	v_exp_f32_e32 v164, v164
	v_exp_f32_e32 v165, v165
	v_exp_f32_e32 v166, v166
	v_exp_f32_e32 v167, v167
	v_exp_f32_e32 v168, v168
	v_exp_f32_e32 v169, v169
	v_pk_add_f32 v[162:163], v[162:163], 1.0 op_sel_hi:[1,0]
	v_pk_add_f32 v[164:165], v[164:165], 1.0 op_sel_hi:[1,0]
	v_pk_add_f32 v[166:167], v[166:167], 1.0 op_sel_hi:[1,0]
	v_pk_add_f32 v[168:169], v[168:169], 1.0 op_sel_hi:[1,0]
	v_rcp_f32_e32 v162, v162
	v_rcp_f32_e32 v163, v163
	v_rcp_f32_e32 v164, v164
	v_rcp_f32_e32 v165, v165
	v_rcp_f32_e32 v166, v166
	v_rcp_f32_e32 v167, v167
	v_rcp_f32_e32 v168, v168
	v_rcp_f32_e32 v169, v169
	v_pk_mul_f32 v[162:163], v[110:111], v[162:163]
	v_pk_mul_f32 v[164:165], v[112:113], v[164:165]
	v_pk_mul_f32 v[166:167], v[106:107], v[166:167]
	v_pk_mul_f32 v[168:169], v[108:109], v[168:169]
	v_cvt_pk_bf16_f32 v170, v162, v163
	v_cvt_pk_bf16_f32 v171, v164, v165
	v_cvt_pk_bf16_f32 v172, v166, v167
	v_cvt_pk_bf16_f32 v173, v168, v169
	ds_bpermute_b32 v174, v157, v170
	ds_bpermute_b32 v175, v157, v171
	ds_bpermute_b32 v176, v157, v172
	ds_bpermute_b32 v177, v157, v173
	s_waitcnt lgkmcnt(4)
	global_store_dwordx4 v[184:185], v[178:181], off offset:256
	s_mov_b32 s10, 0x8000
	s_mov_b32 s11, 0
	v_lshl_add_u64 v[182:183], v[184:185], 0, s[10:11]
	v_pk_mul_f32 v[162:163], v[102:103], s[100:101]
	v_pk_mul_f32 v[164:165], v[104:105], s[100:101]
	v_pk_mul_f32 v[166:167], v[98:99], s[100:101]
	v_pk_mul_f32 v[168:169], v[100:101], s[100:101]
	v_exp_f32_e32 v162, v162
	v_exp_f32_e32 v163, v163
	v_exp_f32_e32 v164, v164
	v_exp_f32_e32 v165, v165
	v_exp_f32_e32 v166, v166
	v_exp_f32_e32 v167, v167
	v_exp_f32_e32 v168, v168
	v_exp_f32_e32 v169, v169
	v_pk_add_f32 v[162:163], v[162:163], 1.0 op_sel_hi:[1,0]
	v_pk_add_f32 v[164:165], v[164:165], 1.0 op_sel_hi:[1,0]
	v_pk_add_f32 v[166:167], v[166:167], 1.0 op_sel_hi:[1,0]
	v_pk_add_f32 v[168:169], v[168:169], 1.0 op_sel_hi:[1,0]
	v_rcp_f32_e32 v162, v162
	v_rcp_f32_e32 v163, v163
	v_rcp_f32_e32 v164, v164
	v_rcp_f32_e32 v165, v165
	v_rcp_f32_e32 v166, v166
	v_rcp_f32_e32 v167, v167
	v_rcp_f32_e32 v168, v168
	v_rcp_f32_e32 v169, v169
	v_pk_mul_f32 v[162:163], v[102:103], v[162:163]
	v_pk_mul_f32 v[164:165], v[104:105], v[164:165]
	v_pk_mul_f32 v[166:167], v[98:99], v[166:167]
	v_pk_mul_f32 v[168:169], v[100:101], v[168:169]
	v_cvt_pk_bf16_f32 v170, v162, v163
	v_cvt_pk_bf16_f32 v171, v164, v165
	v_cvt_pk_bf16_f32 v172, v166, v167
	v_cvt_pk_bf16_f32 v173, v168, v169
	ds_bpermute_b32 v178, v157, v170
	ds_bpermute_b32 v179, v157, v171
	ds_bpermute_b32 v180, v157, v172
	ds_bpermute_b32 v181, v157, v173
	s_waitcnt lgkmcnt(4)
	global_store_dwordx4 v[182:183], v[174:177], off
	v_pk_mul_f32 v[162:163], v[94:95], s[100:101]
	v_pk_mul_f32 v[164:165], v[96:97], s[100:101]
	v_pk_mul_f32 v[166:167], v[90:91], s[100:101]
	v_pk_mul_f32 v[168:169], v[92:93], s[100:101]
	v_exp_f32_e32 v162, v162
	v_exp_f32_e32 v163, v163
	v_exp_f32_e32 v164, v164
	v_exp_f32_e32 v165, v165
	v_exp_f32_e32 v166, v166
	v_exp_f32_e32 v167, v167
	v_exp_f32_e32 v168, v168
	v_exp_f32_e32 v169, v169
	v_pk_add_f32 v[162:163], v[162:163], 1.0 op_sel_hi:[1,0]
	v_pk_add_f32 v[164:165], v[164:165], 1.0 op_sel_hi:[1,0]
	v_pk_add_f32 v[166:167], v[166:167], 1.0 op_sel_hi:[1,0]
	v_pk_add_f32 v[168:169], v[168:169], 1.0 op_sel_hi:[1,0]
	v_rcp_f32_e32 v162, v162
	v_rcp_f32_e32 v163, v163
	v_rcp_f32_e32 v164, v164
	v_rcp_f32_e32 v165, v165
	v_rcp_f32_e32 v166, v166
	v_rcp_f32_e32 v167, v167
	v_rcp_f32_e32 v168, v168
	v_rcp_f32_e32 v169, v169
	v_pk_mul_f32 v[162:163], v[94:95], v[162:163]
	v_pk_mul_f32 v[164:165], v[96:97], v[164:165]
	v_pk_mul_f32 v[166:167], v[90:91], v[166:167]
	v_pk_mul_f32 v[168:169], v[92:93], v[168:169]
	v_cvt_pk_bf16_f32 v170, v162, v163
	v_cvt_pk_bf16_f32 v171, v164, v165
	v_cvt_pk_bf16_f32 v172, v166, v167
	v_cvt_pk_bf16_f32 v173, v168, v169
	ds_bpermute_b32 v174, v157, v170
	ds_bpermute_b32 v175, v157, v171
	ds_bpermute_b32 v176, v157, v172
	ds_bpermute_b32 v177, v157, v173
	s_waitcnt lgkmcnt(4)
	global_store_dwordx4 v[182:183], v[178:181], off offset:256
	s_mov_b32 s10, 0x10000
	s_mov_b32 s11, 0
	v_lshl_add_u64 v[182:183], v[184:185], 0, s[10:11]
	v_pk_mul_f32 v[162:163], v[86:87], s[100:101]
	v_pk_mul_f32 v[164:165], v[88:89], s[100:101]
	v_pk_mul_f32 v[166:167], v[82:83], s[100:101]
	v_pk_mul_f32 v[168:169], v[84:85], s[100:101]
	v_exp_f32_e32 v162, v162
	v_exp_f32_e32 v163, v163
	v_exp_f32_e32 v164, v164
	v_exp_f32_e32 v165, v165
	v_exp_f32_e32 v166, v166
	v_exp_f32_e32 v167, v167
	v_exp_f32_e32 v168, v168
	v_exp_f32_e32 v169, v169
	v_pk_add_f32 v[162:163], v[162:163], 1.0 op_sel_hi:[1,0]
	v_pk_add_f32 v[164:165], v[164:165], 1.0 op_sel_hi:[1,0]
	v_pk_add_f32 v[166:167], v[166:167], 1.0 op_sel_hi:[1,0]
	v_pk_add_f32 v[168:169], v[168:169], 1.0 op_sel_hi:[1,0]
	v_rcp_f32_e32 v162, v162
	v_rcp_f32_e32 v163, v163
	v_rcp_f32_e32 v164, v164
	v_rcp_f32_e32 v165, v165
	v_rcp_f32_e32 v166, v166
	v_rcp_f32_e32 v167, v167
	v_rcp_f32_e32 v168, v168
	v_rcp_f32_e32 v169, v169
	v_pk_mul_f32 v[162:163], v[86:87], v[162:163]
	v_pk_mul_f32 v[164:165], v[88:89], v[164:165]
	v_pk_mul_f32 v[166:167], v[82:83], v[166:167]
	v_pk_mul_f32 v[168:169], v[84:85], v[168:169]
	v_cvt_pk_bf16_f32 v170, v162, v163
	v_cvt_pk_bf16_f32 v171, v164, v165
	v_cvt_pk_bf16_f32 v172, v166, v167
	v_cvt_pk_bf16_f32 v173, v168, v169
	ds_bpermute_b32 v178, v157, v170
	ds_bpermute_b32 v179, v157, v171
	ds_bpermute_b32 v180, v157, v172
	ds_bpermute_b32 v181, v157, v173
	s_waitcnt lgkmcnt(4)
; #define GAS __attribute__((address_space(1)))
; __device__ __forceinline__ float fast_exp2(float x) { return __builtin_amdgcn_exp2f(x); }
; __device__ __forceinline__ float fast_rcp(float x) { return __builtin_amdgcn_rcpf(x); }
; __device__ __forceinline__ v4u tr4(int a, v4u x) { return (v4u){bperm(a, x.x), bperm(a, x.y), bperm(a, x.z), bperm(a, x.w)}; }
; __device__ __forceinline__ v4u pack8(const f32x4& a, const f32x4& b) { return (v4u){pg8::cvt_pk_bf16(a[0], a[1]), pg8::cvt_pk_bf16(a[2], a[3]), pg8::cvt_pk_bf16(b[0], b[1]), pg8::cvt_pk_bf16(b[2], b[3])}; }
; __device__ __forceinline__ float sigmoidf_(float x) { return fast_rcp(1.0f + fast_exp2(-x * LOG2E)); }
; __device__ __forceinline__ float siluf_(float x) { return x * sigmoidf_(x); }
;     __device__ __forceinline__ bool operator()(AccT& acc, const Unit& u, int wr, int wc, int fr, int fq) const {
;     ...
;         if (seg == 0 || seg == 1 || seg == 2 || seg >= 6) {
;             bf16* dst = (bf16*)(ws + (seg == 0 ? WS_VR : seg == 1 ? WS_GR : seg == 2 ? WS_QS : WS_GT)); const int ld = seg >= 6 ? 3 * D : D; const int cofs = seg >= 6 ? (seg - 6) * D : 0;
; #pragma unroll
;             for (int ai = 0; ai < 2; ++ai)
; #pragma unroll
;                 for (int m = 0; m < 4; ++m) { const size_t r = (size_t)(pm * 256 + trl0 + ai * 128 + m * 16);
; #pragma unroll
;                     for (int bj = 0; bj < 2; ++bj) { f32x4 v0 = acc[ai][bj][m][0], v1 = acc[ai][bj][m][1];
;                         if (seg == 1) {
; #pragma unroll
;                             for (int e = 0; e < 4; ++e) { v0[e] = siluf_(v0[e]); v1[e] = siluf_(v1[e]); } }
;                         else if (seg == 2) { v0 = v0 * (0.08838834764831845f * LOG2E); v1 = v1 * (0.08838834764831845f * LOG2E); }
;                         else if (seg >= 6) {
; #pragma unroll
;                             for (int e = 0; e < 4; ++e) { v0[e] = sigmoidf_(v0[e]); v1[e] = sigmoidf_(v1[e]); } }
;                         *(GAS v4u*)(dst + r * ld + cofs + colt + bj * 128) = tr4(t.pull, pack8(v0, v1)); } }
	global_store_dwordx4 v[182:183], v[174:177], off
	v_pk_mul_f32 v[162:163], v[78:79], s[100:101]
	v_pk_mul_f32 v[164:165], v[80:81], s[100:101]
	v_pk_mul_f32 v[166:167], v[74:75], s[100:101]
	v_pk_mul_f32 v[168:169], v[76:77], s[100:101]
	v_exp_f32_e32 v162, v162
	v_exp_f32_e32 v163, v163
	v_exp_f32_e32 v164, v164
	v_exp_f32_e32 v165, v165
	v_exp_f32_e32 v166, v166
	v_exp_f32_e32 v167, v167
	v_exp_f32_e32 v168, v168
	v_exp_f32_e32 v169, v169
	v_pk_add_f32 v[162:163], v[162:163], 1.0 op_sel_hi:[1,0]
	v_pk_add_f32 v[164:165], v[164:165], 1.0 op_sel_hi:[1,0]
	v_pk_add_f32 v[166:167], v[166:167], 1.0 op_sel_hi:[1,0]
	v_pk_add_f32 v[168:169], v[168:169], 1.0 op_sel_hi:[1,0]
	v_rcp_f32_e32 v162, v162
	v_rcp_f32_e32 v163, v163
	v_rcp_f32_e32 v164, v164
	v_rcp_f32_e32 v165, v165
	v_rcp_f32_e32 v166, v166
	v_rcp_f32_e32 v167, v167
	v_rcp_f32_e32 v168, v168
	v_rcp_f32_e32 v169, v169
	v_pk_mul_f32 v[162:163], v[78:79], v[162:163]
	v_pk_mul_f32 v[164:165], v[80:81], v[164:165]
	v_pk_mul_f32 v[166:167], v[74:75], v[166:167]
	v_pk_mul_f32 v[168:169], v[76:77], v[168:169]
	v_cvt_pk_bf16_f32 v170, v162, v163
	v_cvt_pk_bf16_f32 v171, v164, v165
	v_cvt_pk_bf16_f32 v172, v166, v167
	v_cvt_pk_bf16_f32 v173, v168, v169
	ds_bpermute_b32 v174, v157, v170
	ds_bpermute_b32 v175, v157, v171
	ds_bpermute_b32 v176, v157, v172
	ds_bpermute_b32 v177, v157, v173
	s_waitcnt lgkmcnt(4)
	global_store_dwordx4 v[182:183], v[178:181], off offset:256
	s_mov_b32 s10, 0x18000
	s_mov_b32 s11, 0
	v_lshl_add_u64 v[182:183], v[184:185], 0, s[10:11]
	v_pk_mul_f32 v[162:163], v[70:71], s[100:101]
	v_pk_mul_f32 v[164:165], v[72:73], s[100:101]
	v_pk_mul_f32 v[166:167], v[66:67], s[100:101]
	v_pk_mul_f32 v[168:169], v[68:69], s[100:101]
	v_exp_f32_e32 v162, v162
	v_exp_f32_e32 v163, v163
	v_exp_f32_e32 v164, v164
	v_exp_f32_e32 v165, v165
	v_exp_f32_e32 v166, v166
	v_exp_f32_e32 v167, v167
	v_exp_f32_e32 v168, v168
	v_exp_f32_e32 v169, v169
	v_pk_add_f32 v[162:163], v[162:163], 1.0 op_sel_hi:[1,0]
	v_pk_add_f32 v[164:165], v[164:165], 1.0 op_sel_hi:[1,0]
	v_pk_add_f32 v[166:167], v[166:167], 1.0 op_sel_hi:[1,0]
	v_pk_add_f32 v[168:169], v[168:169], 1.0 op_sel_hi:[1,0]
	v_rcp_f32_e32 v162, v162
	v_rcp_f32_e32 v163, v163
	v_rcp_f32_e32 v164, v164
	v_rcp_f32_e32 v165, v165
	v_rcp_f32_e32 v166, v166
	v_rcp_f32_e32 v167, v167
	v_rcp_f32_e32 v168, v168
	v_rcp_f32_e32 v169, v169
	v_pk_mul_f32 v[162:163], v[70:71], v[162:163]
	v_pk_mul_f32 v[164:165], v[72:73], v[164:165]
	v_pk_mul_f32 v[166:167], v[66:67], v[166:167]
	v_pk_mul_f32 v[168:169], v[68:69], v[168:169]
	v_cvt_pk_bf16_f32 v170, v162, v163
	v_cvt_pk_bf16_f32 v171, v164, v165
	v_cvt_pk_bf16_f32 v172, v166, v167
	v_cvt_pk_bf16_f32 v173, v168, v169
	ds_bpermute_b32 v178, v157, v170
	ds_bpermute_b32 v179, v157, v171
	ds_bpermute_b32 v180, v157, v172
	ds_bpermute_b32 v181, v157, v173
	s_waitcnt lgkmcnt(4)
	global_store_dwordx4 v[182:183], v[174:177], off
	v_pk_mul_f32 v[162:163], v[62:63], s[100:101]
	v_pk_mul_f32 v[164:165], v[64:65], s[100:101]
	v_pk_mul_f32 v[166:167], v[58:59], s[100:101]
	v_pk_mul_f32 v[168:169], v[60:61], s[100:101]
	v_exp_f32_e32 v162, v162
	v_exp_f32_e32 v163, v163
	v_exp_f32_e32 v164, v164
	v_exp_f32_e32 v165, v165
	v_exp_f32_e32 v166, v166
	v_exp_f32_e32 v167, v167
	v_exp_f32_e32 v168, v168
	v_exp_f32_e32 v169, v169
	v_pk_add_f32 v[162:163], v[162:163], 1.0 op_sel_hi:[1,0]
	v_pk_add_f32 v[164:165], v[164:165], 1.0 op_sel_hi:[1,0]
	v_pk_add_f32 v[166:167], v[166:167], 1.0 op_sel_hi:[1,0]
	v_pk_add_f32 v[168:169], v[168:169], 1.0 op_sel_hi:[1,0]
	v_rcp_f32_e32 v162, v162
	v_rcp_f32_e32 v163, v163
	v_rcp_f32_e32 v164, v164
	v_rcp_f32_e32 v165, v165
	v_rcp_f32_e32 v166, v166
	v_rcp_f32_e32 v167, v167
	v_rcp_f32_e32 v168, v168
	v_rcp_f32_e32 v169, v169
	v_pk_mul_f32 v[162:163], v[62:63], v[162:163]
	v_pk_mul_f32 v[164:165], v[64:65], v[164:165]
	v_pk_mul_f32 v[166:167], v[58:59], v[166:167]
	v_pk_mul_f32 v[168:169], v[60:61], v[168:169]
	v_cvt_pk_bf16_f32 v170, v162, v163
	v_cvt_pk_bf16_f32 v171, v164, v165
	v_cvt_pk_bf16_f32 v172, v166, v167
	v_cvt_pk_bf16_f32 v173, v168, v169
	ds_bpermute_b32 v174, v157, v170
	ds_bpermute_b32 v175, v157, v171
	ds_bpermute_b32 v176, v157, v172
	ds_bpermute_b32 v177, v157, v173
	s_waitcnt lgkmcnt(4)
	global_store_dwordx4 v[182:183], v[178:181], off offset:256
	s_mov_b32 s10, 0x40000
	s_mov_b32 s11, 0
	v_lshl_add_u64 v[182:183], v[184:185], 0, s[10:11]
	v_pk_mul_f32 v[162:163], v[54:55], s[100:101]
	v_pk_mul_f32 v[164:165], v[56:57], s[100:101]
	v_pk_mul_f32 v[166:167], v[50:51], s[100:101]
	v_pk_mul_f32 v[168:169], v[52:53], s[100:101]
	v_exp_f32_e32 v162, v162
	v_exp_f32_e32 v163, v163
	v_exp_f32_e32 v164, v164
	v_exp_f32_e32 v165, v165
	v_exp_f32_e32 v166, v166
	v_exp_f32_e32 v167, v167
	v_exp_f32_e32 v168, v168
	v_exp_f32_e32 v169, v169
	v_pk_add_f32 v[162:163], v[162:163], 1.0 op_sel_hi:[1,0]
	v_pk_add_f32 v[164:165], v[164:165], 1.0 op_sel_hi:[1,0]
	v_pk_add_f32 v[166:167], v[166:167], 1.0 op_sel_hi:[1,0]
	v_pk_add_f32 v[168:169], v[168:169], 1.0 op_sel_hi:[1,0]
	v_rcp_f32_e32 v162, v162
	v_rcp_f32_e32 v163, v163
	v_rcp_f32_e32 v164, v164
	v_rcp_f32_e32 v165, v165
	v_rcp_f32_e32 v166, v166
	v_rcp_f32_e32 v167, v167
	v_rcp_f32_e32 v168, v168
	v_rcp_f32_e32 v169, v169
	v_pk_mul_f32 v[162:163], v[54:55], v[162:163]
	v_pk_mul_f32 v[164:165], v[56:57], v[164:165]
	v_pk_mul_f32 v[166:167], v[50:51], v[166:167]
	v_pk_mul_f32 v[168:169], v[52:53], v[168:169]
	v_cvt_pk_bf16_f32 v170, v162, v163
	v_cvt_pk_bf16_f32 v171, v164, v165
	v_cvt_pk_bf16_f32 v172, v166, v167
	v_cvt_pk_bf16_f32 v173, v168, v169
	ds_bpermute_b32 v178, v157, v170
	ds_bpermute_b32 v179, v157, v171
	ds_bpermute_b32 v180, v157, v172
	ds_bpermute_b32 v181, v157, v173
	s_waitcnt lgkmcnt(4)
; #define GAS __attribute__((address_space(1)))
; __device__ __forceinline__ float fast_exp2(float x) { return __builtin_amdgcn_exp2f(x); }
; __device__ __forceinline__ float fast_rcp(float x) { return __builtin_amdgcn_rcpf(x); }
; __device__ __forceinline__ v4u tr4(int a, v4u x) { return (v4u){bperm(a, x.x), bperm(a, x.y), bperm(a, x.z), bperm(a, x.w)}; }
; __device__ __forceinline__ v4u pack8(const f32x4& a, const f32x4& b) { return (v4u){pg8::cvt_pk_bf16(a[0], a[1]), pg8::cvt_pk_bf16(a[2], a[3]), pg8::cvt_pk_bf16(b[0], b[1]), pg8::cvt_pk_bf16(b[2], b[3])}; }
; __device__ __forceinline__ float sigmoidf_(float x) { return fast_rcp(1.0f + fast_exp2(-x * LOG2E)); }
; __device__ __forceinline__ float siluf_(float x) { return x * sigmoidf_(x); }
;     __device__ __forceinline__ bool operator()(AccT& acc, const Unit& u, int wr, int wc, int fr, int fq) const {
;     ...
;         if (seg == 0 || seg == 1 || seg == 2 || seg >= 6) {
;             bf16* dst = (bf16*)(ws + (seg == 0 ? WS_VR : seg == 1 ? WS_GR : seg == 2 ? WS_QS : WS_GT)); const int ld = seg >= 6 ? 3 * D : D; const int cofs = seg >= 6 ? (seg - 6) * D : 0;
; #pragma unroll
;             for (int ai = 0; ai < 2; ++ai)
; #pragma unroll
;                 for (int m = 0; m < 4; ++m) { const size_t r = (size_t)(pm * 256 + trl0 + ai * 128 + m * 16);
; #pragma unroll
;                     for (int bj = 0; bj < 2; ++bj) { f32x4 v0 = acc[ai][bj][m][0], v1 = acc[ai][bj][m][1];
;                         if (seg == 1) {
; #pragma unroll
;                             for (int e = 0; e < 4; ++e) { v0[e] = siluf_(v0[e]); v1[e] = siluf_(v1[e]); } }
;                         else if (seg == 2) { v0 = v0 * (0.08838834764831845f * LOG2E); v1 = v1 * (0.08838834764831845f * LOG2E); }
;                         else if (seg >= 6) {
; #pragma unroll
;                             for (int e = 0; e < 4; ++e) { v0[e] = sigmoidf_(v0[e]); v1[e] = sigmoidf_(v1[e]); } }
;                         *(GAS v4u*)(dst + r * ld + cofs + colt + bj * 128) = tr4(t.pull, pack8(v0, v1)); } }
	global_store_dwordx4 v[182:183], v[174:177], off
	v_pk_mul_f32 v[162:163], v[46:47], s[100:101]
	v_pk_mul_f32 v[164:165], v[48:49], s[100:101]
	v_pk_mul_f32 v[166:167], v[42:43], s[100:101]
	v_pk_mul_f32 v[168:169], v[44:45], s[100:101]
	v_exp_f32_e32 v162, v162
	v_exp_f32_e32 v163, v163
	v_exp_f32_e32 v164, v164
	v_exp_f32_e32 v165, v165
	v_exp_f32_e32 v166, v166
	v_exp_f32_e32 v167, v167
	v_exp_f32_e32 v168, v168
	v_exp_f32_e32 v169, v169
	v_pk_add_f32 v[162:163], v[162:163], 1.0 op_sel_hi:[1,0]
	v_pk_add_f32 v[164:165], v[164:165], 1.0 op_sel_hi:[1,0]
	v_pk_add_f32 v[166:167], v[166:167], 1.0 op_sel_hi:[1,0]
	v_pk_add_f32 v[168:169], v[168:169], 1.0 op_sel_hi:[1,0]
	v_rcp_f32_e32 v162, v162
	v_rcp_f32_e32 v163, v163
	v_rcp_f32_e32 v164, v164
	v_rcp_f32_e32 v165, v165
	v_rcp_f32_e32 v166, v166
	v_rcp_f32_e32 v167, v167
	v_rcp_f32_e32 v168, v168
	v_rcp_f32_e32 v169, v169
	v_pk_mul_f32 v[162:163], v[46:47], v[162:163]
	v_pk_mul_f32 v[164:165], v[48:49], v[164:165]
	v_pk_mul_f32 v[166:167], v[42:43], v[166:167]
	v_pk_mul_f32 v[168:169], v[44:45], v[168:169]
	v_cvt_pk_bf16_f32 v170, v162, v163
	v_cvt_pk_bf16_f32 v171, v164, v165
	v_cvt_pk_bf16_f32 v172, v166, v167
	v_cvt_pk_bf16_f32 v173, v168, v169
	ds_bpermute_b32 v174, v157, v170
	ds_bpermute_b32 v175, v157, v171
	ds_bpermute_b32 v176, v157, v172
	ds_bpermute_b32 v177, v157, v173
	s_waitcnt lgkmcnt(4)
	global_store_dwordx4 v[182:183], v[178:181], off offset:256
	s_mov_b32 s10, 0x48000
	s_mov_b32 s11, 0
	v_lshl_add_u64 v[182:183], v[184:185], 0, s[10:11]
	v_pk_mul_f32 v[162:163], v[38:39], s[100:101]
	v_pk_mul_f32 v[164:165], v[40:41], s[100:101]
	v_pk_mul_f32 v[166:167], v[34:35], s[100:101]
	v_pk_mul_f32 v[168:169], v[36:37], s[100:101]
	v_exp_f32_e32 v162, v162
	v_exp_f32_e32 v163, v163
	v_exp_f32_e32 v164, v164
	v_exp_f32_e32 v165, v165
	v_exp_f32_e32 v166, v166
	v_exp_f32_e32 v167, v167
	v_exp_f32_e32 v168, v168
	v_exp_f32_e32 v169, v169
	v_pk_add_f32 v[162:163], v[162:163], 1.0 op_sel_hi:[1,0]
	v_pk_add_f32 v[164:165], v[164:165], 1.0 op_sel_hi:[1,0]
	v_pk_add_f32 v[166:167], v[166:167], 1.0 op_sel_hi:[1,0]
	v_pk_add_f32 v[168:169], v[168:169], 1.0 op_sel_hi:[1,0]
	v_rcp_f32_e32 v162, v162
	v_rcp_f32_e32 v163, v163
	v_rcp_f32_e32 v164, v164
	v_rcp_f32_e32 v165, v165
	v_rcp_f32_e32 v166, v166
	v_rcp_f32_e32 v167, v167
	v_rcp_f32_e32 v168, v168
	v_rcp_f32_e32 v169, v169
	v_pk_mul_f32 v[162:163], v[38:39], v[162:163]
	v_pk_mul_f32 v[164:165], v[40:41], v[164:165]
	v_pk_mul_f32 v[166:167], v[34:35], v[166:167]
	v_pk_mul_f32 v[168:169], v[36:37], v[168:169]
	v_cvt_pk_bf16_f32 v170, v162, v163
	v_cvt_pk_bf16_f32 v171, v164, v165
	v_cvt_pk_bf16_f32 v172, v166, v167
	v_cvt_pk_bf16_f32 v173, v168, v169
	ds_bpermute_b32 v178, v157, v170
	ds_bpermute_b32 v179, v157, v171
	ds_bpermute_b32 v180, v157, v172
	ds_bpermute_b32 v181, v157, v173
	s_waitcnt lgkmcnt(4)
	global_store_dwordx4 v[182:183], v[174:177], off
	v_pk_mul_f32 v[162:163], v[30:31], s[100:101]
	v_pk_mul_f32 v[164:165], v[32:33], s[100:101]
	v_pk_mul_f32 v[166:167], v[26:27], s[100:101]
	v_pk_mul_f32 v[168:169], v[28:29], s[100:101]
	v_exp_f32_e32 v162, v162
	v_exp_f32_e32 v163, v163
	v_exp_f32_e32 v164, v164
	v_exp_f32_e32 v165, v165
	v_exp_f32_e32 v166, v166
	v_exp_f32_e32 v167, v167
	v_exp_f32_e32 v168, v168
	v_exp_f32_e32 v169, v169
	v_pk_add_f32 v[162:163], v[162:163], 1.0 op_sel_hi:[1,0]
	v_pk_add_f32 v[164:165], v[164:165], 1.0 op_sel_hi:[1,0]
	v_pk_add_f32 v[166:167], v[166:167], 1.0 op_sel_hi:[1,0]
	v_pk_add_f32 v[168:169], v[168:169], 1.0 op_sel_hi:[1,0]
	v_rcp_f32_e32 v162, v162
	v_rcp_f32_e32 v163, v163
	v_rcp_f32_e32 v164, v164
	v_rcp_f32_e32 v165, v165
	v_rcp_f32_e32 v166, v166
	v_rcp_f32_e32 v167, v167
	v_rcp_f32_e32 v168, v168
	v_rcp_f32_e32 v169, v169
	v_pk_mul_f32 v[162:163], v[30:31], v[162:163]
	v_pk_mul_f32 v[164:165], v[32:33], v[164:165]
	v_pk_mul_f32 v[166:167], v[26:27], v[166:167]
	v_pk_mul_f32 v[168:169], v[28:29], v[168:169]
	v_cvt_pk_bf16_f32 v170, v162, v163
	v_cvt_pk_bf16_f32 v171, v164, v165
	v_cvt_pk_bf16_f32 v172, v166, v167
	v_cvt_pk_bf16_f32 v173, v168, v169
	ds_bpermute_b32 v174, v157, v170
	ds_bpermute_b32 v175, v157, v171
	ds_bpermute_b32 v176, v157, v172
	ds_bpermute_b32 v177, v157, v173
	s_waitcnt lgkmcnt(4)
	global_store_dwordx4 v[182:183], v[178:181], off offset:256
	s_mov_b32 s10, 0x50000
	s_mov_b32 s11, 0
	v_lshl_add_u64 v[182:183], v[184:185], 0, s[10:11]
	v_pk_mul_f32 v[162:163], v[22:23], s[100:101]
	v_pk_mul_f32 v[164:165], v[24:25], s[100:101]
	v_pk_mul_f32 v[166:167], v[18:19], s[100:101]
	v_pk_mul_f32 v[168:169], v[20:21], s[100:101]
	v_exp_f32_e32 v162, v162
	v_exp_f32_e32 v163, v163
	v_exp_f32_e32 v164, v164
	v_exp_f32_e32 v165, v165
	v_exp_f32_e32 v166, v166
	v_exp_f32_e32 v167, v167
	v_exp_f32_e32 v168, v168
	v_exp_f32_e32 v169, v169
	v_pk_add_f32 v[162:163], v[162:163], 1.0 op_sel_hi:[1,0]
	v_pk_add_f32 v[164:165], v[164:165], 1.0 op_sel_hi:[1,0]
	v_pk_add_f32 v[166:167], v[166:167], 1.0 op_sel_hi:[1,0]
	v_pk_add_f32 v[168:169], v[168:169], 1.0 op_sel_hi:[1,0]
	v_rcp_f32_e32 v162, v162
	v_rcp_f32_e32 v163, v163
	v_rcp_f32_e32 v164, v164
	v_rcp_f32_e32 v165, v165
	v_rcp_f32_e32 v166, v166
	v_rcp_f32_e32 v167, v167
	v_rcp_f32_e32 v168, v168
	v_rcp_f32_e32 v169, v169
	v_pk_mul_f32 v[162:163], v[22:23], v[162:163]
	v_pk_mul_f32 v[164:165], v[24:25], v[164:165]
	v_pk_mul_f32 v[166:167], v[18:19], v[166:167]
	v_pk_mul_f32 v[168:169], v[20:21], v[168:169]
	v_cvt_pk_bf16_f32 v170, v162, v163
	v_cvt_pk_bf16_f32 v171, v164, v165
	v_cvt_pk_bf16_f32 v172, v166, v167
	v_cvt_pk_bf16_f32 v173, v168, v169
	ds_bpermute_b32 v178, v157, v170
	ds_bpermute_b32 v179, v157, v171
	ds_bpermute_b32 v180, v157, v172
	ds_bpermute_b32 v181, v157, v173
	s_waitcnt lgkmcnt(4)
; #define GAS __attribute__((address_space(1)))
; __device__ __forceinline__ float fast_exp2(float x) { return __builtin_amdgcn_exp2f(x); }
; __device__ __forceinline__ float fast_rcp(float x) { return __builtin_amdgcn_rcpf(x); }
; __device__ __forceinline__ v4u tr4(int a, v4u x) { return (v4u){bperm(a, x.x), bperm(a, x.y), bperm(a, x.z), bperm(a, x.w)}; }
; __device__ __forceinline__ v4u pack8(const f32x4& a, const f32x4& b) { return (v4u){pg8::cvt_pk_bf16(a[0], a[1]), pg8::cvt_pk_bf16(a[2], a[3]), pg8::cvt_pk_bf16(b[0], b[1]), pg8::cvt_pk_bf16(b[2], b[3])}; }
; __device__ __forceinline__ float sigmoidf_(float x) { return fast_rcp(1.0f + fast_exp2(-x * LOG2E)); }
; __device__ __forceinline__ float siluf_(float x) { return x * sigmoidf_(x); }
;     __device__ __forceinline__ bool operator()(AccT& acc, const Unit& u, int wr, int wc, int fr, int fq) const {
;     ...
;         if (seg == 0 || seg == 1 || seg == 2 || seg >= 6) {
;             bf16* dst = (bf16*)(ws + (seg == 0 ? WS_VR : seg == 1 ? WS_GR : seg == 2 ? WS_QS : WS_GT)); const int ld = seg >= 6 ? 3 * D : D; const int cofs = seg >= 6 ? (seg - 6) * D : 0;
; #pragma unroll
;             for (int ai = 0; ai < 2; ++ai)
; #pragma unroll
;                 for (int m = 0; m < 4; ++m) { const size_t r = (size_t)(pm * 256 + trl0 + ai * 128 + m * 16);
; #pragma unroll
;                     for (int bj = 0; bj < 2; ++bj) { f32x4 v0 = acc[ai][bj][m][0], v1 = acc[ai][bj][m][1];
;                         if (seg == 1) {
; #pragma unroll
;                             for (int e = 0; e < 4; ++e) { v0[e] = siluf_(v0[e]); v1[e] = siluf_(v1[e]); } }
;                         else if (seg == 2) { v0 = v0 * (0.08838834764831845f * LOG2E); v1 = v1 * (0.08838834764831845f * LOG2E); }
;                         else if (seg >= 6) {
; #pragma unroll
;                             for (int e = 0; e < 4; ++e) { v0[e] = sigmoidf_(v0[e]); v1[e] = sigmoidf_(v1[e]); } }
;                         *(GAS v4u*)(dst + r * ld + cofs + colt + bj * 128) = tr4(t.pull, pack8(v0, v1)); } }
	global_store_dwordx4 v[182:183], v[174:177], off
	v_pk_mul_f32 v[162:163], v[14:15], s[100:101]
	v_pk_mul_f32 v[164:165], v[16:17], s[100:101]
	v_pk_mul_f32 v[166:167], v[10:11], s[100:101]
	v_pk_mul_f32 v[168:169], v[12:13], s[100:101]
	v_exp_f32_e32 v162, v162
	v_exp_f32_e32 v163, v163
	v_exp_f32_e32 v164, v164
	v_exp_f32_e32 v165, v165
	v_exp_f32_e32 v166, v166
	v_exp_f32_e32 v167, v167
	v_exp_f32_e32 v168, v168
	v_exp_f32_e32 v169, v169
	v_pk_add_f32 v[162:163], v[162:163], 1.0 op_sel_hi:[1,0]
	v_pk_add_f32 v[164:165], v[164:165], 1.0 op_sel_hi:[1,0]
	v_pk_add_f32 v[166:167], v[166:167], 1.0 op_sel_hi:[1,0]
	v_pk_add_f32 v[168:169], v[168:169], 1.0 op_sel_hi:[1,0]
	v_rcp_f32_e32 v162, v162
	v_rcp_f32_e32 v163, v163
	v_rcp_f32_e32 v164, v164
	v_rcp_f32_e32 v165, v165
	v_rcp_f32_e32 v166, v166
	v_rcp_f32_e32 v167, v167
	v_rcp_f32_e32 v168, v168
	v_rcp_f32_e32 v169, v169
	v_pk_mul_f32 v[162:163], v[14:15], v[162:163]
	v_pk_mul_f32 v[164:165], v[16:17], v[164:165]
	v_pk_mul_f32 v[166:167], v[10:11], v[166:167]
	v_pk_mul_f32 v[168:169], v[12:13], v[168:169]
	v_cvt_pk_bf16_f32 v170, v162, v163
	v_cvt_pk_bf16_f32 v171, v164, v165
	v_cvt_pk_bf16_f32 v172, v166, v167
	v_cvt_pk_bf16_f32 v173, v168, v169
	ds_bpermute_b32 v174, v157, v170
	ds_bpermute_b32 v175, v157, v171
	ds_bpermute_b32 v176, v157, v172
	ds_bpermute_b32 v177, v157, v173
	s_waitcnt lgkmcnt(4)
	global_store_dwordx4 v[182:183], v[178:181], off offset:256
	s_mov_b32 s10, 0x58000
	s_mov_b32 s11, 0
	v_lshl_add_u64 v[182:183], v[184:185], 0, s[10:11]
	v_pk_mul_f32 v[162:163], v[6:7], s[100:101]
	v_pk_mul_f32 v[164:165], v[8:9], s[100:101]
	v_pk_mul_f32 v[166:167], v[2:3], s[100:101]
	v_pk_mul_f32 v[168:169], v[4:5], s[100:101]
	v_exp_f32_e32 v162, v162
	v_exp_f32_e32 v163, v163
	v_exp_f32_e32 v164, v164
	v_exp_f32_e32 v165, v165
	v_exp_f32_e32 v166, v166
	v_exp_f32_e32 v167, v167
	v_exp_f32_e32 v168, v168
	v_exp_f32_e32 v169, v169
	v_pk_add_f32 v[162:163], v[162:163], 1.0 op_sel_hi:[1,0]
	v_pk_add_f32 v[164:165], v[164:165], 1.0 op_sel_hi:[1,0]
	v_pk_add_f32 v[166:167], v[166:167], 1.0 op_sel_hi:[1,0]
	v_pk_add_f32 v[168:169], v[168:169], 1.0 op_sel_hi:[1,0]
	v_rcp_f32_e32 v162, v162
	v_rcp_f32_e32 v163, v163
	v_rcp_f32_e32 v164, v164
	v_rcp_f32_e32 v165, v165
	v_rcp_f32_e32 v166, v166
	v_rcp_f32_e32 v167, v167
	v_rcp_f32_e32 v168, v168
	v_rcp_f32_e32 v169, v169
	v_pk_mul_f32 v[162:163], v[6:7], v[162:163]
	v_pk_mul_f32 v[164:165], v[8:9], v[164:165]
	v_pk_mul_f32 v[166:167], v[2:3], v[166:167]
	v_pk_mul_f32 v[168:169], v[4:5], v[168:169]
	v_cvt_pk_bf16_f32 v170, v162, v163
	v_cvt_pk_bf16_f32 v171, v164, v165
	v_cvt_pk_bf16_f32 v172, v166, v167
	v_cvt_pk_bf16_f32 v173, v168, v169
	ds_bpermute_b32 v178, v157, v170
	ds_bpermute_b32 v179, v157, v171
	ds_bpermute_b32 v180, v157, v172
	ds_bpermute_b32 v181, v157, v173
	s_waitcnt lgkmcnt(4)
	global_store_dwordx4 v[182:183], v[174:177], off
	s_waitcnt lgkmcnt(0)
	global_store_dwordx4 v[182:183], v[178:181], off offset:256
	s_mov_b64 s[12:13], 0
	s_branch .LBB0_902
.Lwin_not_silu:
	s_cmp_eq_u32 s29, 2
	s_cbranch_scc0 .Lwin_not_scale
	s_mov_b32 s10, 0x3e8c0000
	s_waitcnt lgkmcnt(0)
	s_mov_b32 s100, 0x3e0293ee
	s_mov_b32 s101, 0x3e0293ee
	s_add_u32 s10, s46, s10
	s_addc_u32 s11, s47, 0
	v_lshl_add_u32 v142, s28, 8, v140
	v_ashrrev_i32_e32 v139, 31, v138
	v_lshl_add_u64 v[130:131], v[138:139], 1, s[10:11]
	s_movk_i32 s31, 0x400
	v_mad_i64_i32 v[132:133], s[14:15], s31, v142, 0
	v_lshl_add_u64 v[184:185], v[132:133], 1, v[130:131]
	v_pk_mul_f32 v[162:163], v[126:127], s[100:101]
	v_pk_mul_f32 v[164:165], v[128:129], s[100:101]
	v_pk_mul_f32 v[166:167], v[122:123], s[100:101]
	v_pk_mul_f32 v[168:169], v[124:125], s[100:101]
	v_cvt_pk_bf16_f32 v170, v162, v163
	v_cvt_pk_bf16_f32 v171, v164, v165
	v_cvt_pk_bf16_f32 v172, v166, v167
	v_cvt_pk_bf16_f32 v173, v168, v169
	ds_bpermute_b32 v174, v157, v170
	ds_bpermute_b32 v175, v157, v171
	ds_bpermute_b32 v176, v157, v172
	ds_bpermute_b32 v177, v157, v173
	v_pk_mul_f32 v[162:163], v[118:119], s[100:101]
	v_pk_mul_f32 v[164:165], v[120:121], s[100:101]
	v_pk_mul_f32 v[166:167], v[114:115], s[100:101]
	v_pk_mul_f32 v[168:169], v[116:117], s[100:101]
	v_cvt_pk_bf16_f32 v170, v162, v163
	v_cvt_pk_bf16_f32 v171, v164, v165
	v_cvt_pk_bf16_f32 v172, v166, v167
	v_cvt_pk_bf16_f32 v173, v168, v169
	ds_bpermute_b32 v178, v157, v170
	ds_bpermute_b32 v179, v157, v171
	ds_bpermute_b32 v180, v157, v172
	ds_bpermute_b32 v181, v157, v173
	s_waitcnt lgkmcnt(4)
	global_store_dwordx4 v[184:185], v[174:177], off
	v_pk_mul_f32 v[162:163], v[110:111], s[100:101]
	v_pk_mul_f32 v[164:165], v[112:113], s[100:101]
	v_pk_mul_f32 v[166:167], v[106:107], s[100:101]
	v_pk_mul_f32 v[168:169], v[108:109], s[100:101]
	v_cvt_pk_bf16_f32 v170, v162, v163
	v_cvt_pk_bf16_f32 v171, v164, v165
	v_cvt_pk_bf16_f32 v172, v166, v167
	v_cvt_pk_bf16_f32 v173, v168, v169
	ds_bpermute_b32 v174, v157, v170
	ds_bpermute_b32 v175, v157, v171
	ds_bpermute_b32 v176, v157, v172
	ds_bpermute_b32 v177, v157, v173
	s_waitcnt lgkmcnt(4)
	global_store_dwordx4 v[184:185], v[178:181], off offset:256
	s_mov_b32 s10, 0x8000
	s_mov_b32 s11, 0
	v_lshl_add_u64 v[182:183], v[184:185], 0, s[10:11]
	v_pk_mul_f32 v[162:163], v[102:103], s[100:101]
	v_pk_mul_f32 v[164:165], v[104:105], s[100:101]
	v_pk_mul_f32 v[166:167], v[98:99], s[100:101]
	v_pk_mul_f32 v[168:169], v[100:101], s[100:101]
	v_cvt_pk_bf16_f32 v170, v162, v163
	v_cvt_pk_bf16_f32 v171, v164, v165
	v_cvt_pk_bf16_f32 v172, v166, v167
	v_cvt_pk_bf16_f32 v173, v168, v169
	ds_bpermute_b32 v178, v157, v170
	ds_bpermute_b32 v179, v157, v171
	ds_bpermute_b32 v180, v157, v172
	ds_bpermute_b32 v181, v157, v173
	s_waitcnt lgkmcnt(4)
; #define GAS __attribute__((address_space(1)))
; __device__ __forceinline__ float sigmoidf_(float x) { return fast_rcp(1.0f + fast_exp2(-x * LOG2E)); }
; __device__ __forceinline__ float siluf_(float x) { return x * sigmoidf_(x); }
; __device__ __forceinline__ v4u tr4(int a, v4u x) { return (v4u){bperm(a, x.x), bperm(a, x.y), bperm(a, x.z), bperm(a, x.w)}; }
; __device__ __forceinline__ v4u pack8(const f32x4& a, const f32x4& b) { return (v4u){pg8::cvt_pk_bf16(a[0], a[1]), pg8::cvt_pk_bf16(a[2], a[3]), pg8::cvt_pk_bf16(b[0], b[1]), pg8::cvt_pk_bf16(b[2], b[3])}; }
;     __device__ __forceinline__ bool operator()(AccT& acc, const Unit& u, int wr, int wc, int fr, int fq) const {
;     ...
;         if (seg == 0 || seg == 1 || seg == 2 || seg >= 6) {
;             bf16* dst = (bf16*)(ws + (seg == 0 ? WS_VR : seg == 1 ? WS_GR : seg == 2 ? WS_QS : WS_GT)); const int ld = seg >= 6 ? 3 * D : D; const int cofs = seg >= 6 ? (seg - 6) * D : 0;
; #pragma unroll
;             for (int ai = 0; ai < 2; ++ai)
; #pragma unroll
;                 for (int m = 0; m < 4; ++m) { const size_t r = (size_t)(pm * 256 + trl0 + ai * 128 + m * 16);
; #pragma unroll
;                     for (int bj = 0; bj < 2; ++bj) { f32x4 v0 = acc[ai][bj][m][0], v1 = acc[ai][bj][m][1];
;                         if (seg == 1) {
; #pragma unroll
;                             for (int e = 0; e < 4; ++e) { v0[e] = siluf_(v0[e]); v1[e] = siluf_(v1[e]); } }
;                         else if (seg == 2) { v0 = v0 * (0.08838834764831845f * LOG2E); v1 = v1 * (0.08838834764831845f * LOG2E); }
;                         else if (seg >= 6) {
; #pragma unroll
;                             for (int e = 0; e < 4; ++e) { v0[e] = sigmoidf_(v0[e]); v1[e] = sigmoidf_(v1[e]); } }
;                         *(GAS v4u*)(dst + r * ld + cofs + colt + bj * 128) = tr4(t.pull, pack8(v0, v1)); } }
	global_store_dwordx4 v[182:183], v[174:177], off
	v_pk_mul_f32 v[162:163], v[94:95], s[100:101]
	v_pk_mul_f32 v[164:165], v[96:97], s[100:101]
	v_pk_mul_f32 v[166:167], v[90:91], s[100:101]
	v_pk_mul_f32 v[168:169], v[92:93], s[100:101]
	v_cvt_pk_bf16_f32 v170, v162, v163
	v_cvt_pk_bf16_f32 v171, v164, v165
	v_cvt_pk_bf16_f32 v172, v166, v167
	v_cvt_pk_bf16_f32 v173, v168, v169
	ds_bpermute_b32 v174, v157, v170
	ds_bpermute_b32 v175, v157, v171
	ds_bpermute_b32 v176, v157, v172
	ds_bpermute_b32 v177, v157, v173
	s_waitcnt lgkmcnt(4)
	global_store_dwordx4 v[182:183], v[178:181], off offset:256
	s_mov_b32 s10, 0x10000
	s_mov_b32 s11, 0
	v_lshl_add_u64 v[182:183], v[184:185], 0, s[10:11]
	v_pk_mul_f32 v[162:163], v[86:87], s[100:101]
	v_pk_mul_f32 v[164:165], v[88:89], s[100:101]
	v_pk_mul_f32 v[166:167], v[82:83], s[100:101]
	v_pk_mul_f32 v[168:169], v[84:85], s[100:101]
	v_cvt_pk_bf16_f32 v170, v162, v163
	v_cvt_pk_bf16_f32 v171, v164, v165
	v_cvt_pk_bf16_f32 v172, v166, v167
	v_cvt_pk_bf16_f32 v173, v168, v169
	ds_bpermute_b32 v178, v157, v170
	ds_bpermute_b32 v179, v157, v171
	ds_bpermute_b32 v180, v157, v172
	ds_bpermute_b32 v181, v157, v173
	s_waitcnt lgkmcnt(4)
	global_store_dwordx4 v[182:183], v[174:177], off
	v_pk_mul_f32 v[162:163], v[78:79], s[100:101]
	v_pk_mul_f32 v[164:165], v[80:81], s[100:101]
	v_pk_mul_f32 v[166:167], v[74:75], s[100:101]
	v_pk_mul_f32 v[168:169], v[76:77], s[100:101]
	v_cvt_pk_bf16_f32 v170, v162, v163
	v_cvt_pk_bf16_f32 v171, v164, v165
	v_cvt_pk_bf16_f32 v172, v166, v167
	v_cvt_pk_bf16_f32 v173, v168, v169
	ds_bpermute_b32 v174, v157, v170
	ds_bpermute_b32 v175, v157, v171
	ds_bpermute_b32 v176, v157, v172
	ds_bpermute_b32 v177, v157, v173
	s_waitcnt lgkmcnt(4)
	global_store_dwordx4 v[182:183], v[178:181], off offset:256
	s_mov_b32 s10, 0x18000
	s_mov_b32 s11, 0
	v_lshl_add_u64 v[182:183], v[184:185], 0, s[10:11]
	v_pk_mul_f32 v[162:163], v[70:71], s[100:101]
	v_pk_mul_f32 v[164:165], v[72:73], s[100:101]
	v_pk_mul_f32 v[166:167], v[66:67], s[100:101]
	v_pk_mul_f32 v[168:169], v[68:69], s[100:101]
	v_cvt_pk_bf16_f32 v170, v162, v163
	v_cvt_pk_bf16_f32 v171, v164, v165
	v_cvt_pk_bf16_f32 v172, v166, v167
	v_cvt_pk_bf16_f32 v173, v168, v169
	ds_bpermute_b32 v178, v157, v170
	ds_bpermute_b32 v179, v157, v171
	ds_bpermute_b32 v180, v157, v172
	ds_bpermute_b32 v181, v157, v173
	s_waitcnt lgkmcnt(4)
	global_store_dwordx4 v[182:183], v[174:177], off
	v_pk_mul_f32 v[162:163], v[62:63], s[100:101]
	v_pk_mul_f32 v[164:165], v[64:65], s[100:101]
	v_pk_mul_f32 v[166:167], v[58:59], s[100:101]
	v_pk_mul_f32 v[168:169], v[60:61], s[100:101]
	v_cvt_pk_bf16_f32 v170, v162, v163
	v_cvt_pk_bf16_f32 v171, v164, v165
	v_cvt_pk_bf16_f32 v172, v166, v167
	v_cvt_pk_bf16_f32 v173, v168, v169
	ds_bpermute_b32 v174, v157, v170
	ds_bpermute_b32 v175, v157, v171
	ds_bpermute_b32 v176, v157, v172
	ds_bpermute_b32 v177, v157, v173
	s_waitcnt lgkmcnt(4)
	global_store_dwordx4 v[182:183], v[178:181], off offset:256
	s_mov_b32 s10, 0x40000
	s_mov_b32 s11, 0
	v_lshl_add_u64 v[182:183], v[184:185], 0, s[10:11]
	v_pk_mul_f32 v[162:163], v[54:55], s[100:101]
	v_pk_mul_f32 v[164:165], v[56:57], s[100:101]
	v_pk_mul_f32 v[166:167], v[50:51], s[100:101]
	v_pk_mul_f32 v[168:169], v[52:53], s[100:101]
	v_cvt_pk_bf16_f32 v170, v162, v163
	v_cvt_pk_bf16_f32 v171, v164, v165
	v_cvt_pk_bf16_f32 v172, v166, v167
	v_cvt_pk_bf16_f32 v173, v168, v169
	ds_bpermute_b32 v178, v157, v170
	ds_bpermute_b32 v179, v157, v171
	ds_bpermute_b32 v180, v157, v172
	ds_bpermute_b32 v181, v157, v173
	s_waitcnt lgkmcnt(4)
	global_store_dwordx4 v[182:183], v[174:177], off
	v_pk_mul_f32 v[162:163], v[46:47], s[100:101]
	v_pk_mul_f32 v[164:165], v[48:49], s[100:101]
	v_pk_mul_f32 v[166:167], v[42:43], s[100:101]
	v_pk_mul_f32 v[168:169], v[44:45], s[100:101]
	v_cvt_pk_bf16_f32 v170, v162, v163
	v_cvt_pk_bf16_f32 v171, v164, v165
	v_cvt_pk_bf16_f32 v172, v166, v167
	v_cvt_pk_bf16_f32 v173, v168, v169
	ds_bpermute_b32 v174, v157, v170
	ds_bpermute_b32 v175, v157, v171
	ds_bpermute_b32 v176, v157, v172
	ds_bpermute_b32 v177, v157, v173
	s_waitcnt lgkmcnt(4)
	global_store_dwordx4 v[182:183], v[178:181], off offset:256
	s_mov_b32 s10, 0x48000
	s_mov_b32 s11, 0
	v_lshl_add_u64 v[182:183], v[184:185], 0, s[10:11]
	v_pk_mul_f32 v[162:163], v[38:39], s[100:101]
	v_pk_mul_f32 v[164:165], v[40:41], s[100:101]
	v_pk_mul_f32 v[166:167], v[34:35], s[100:101]
	v_pk_mul_f32 v[168:169], v[36:37], s[100:101]
	v_cvt_pk_bf16_f32 v170, v162, v163
	v_cvt_pk_bf16_f32 v171, v164, v165
	v_cvt_pk_bf16_f32 v172, v166, v167
	v_cvt_pk_bf16_f32 v173, v168, v169
	ds_bpermute_b32 v178, v157, v170
	ds_bpermute_b32 v179, v157, v171
	ds_bpermute_b32 v180, v157, v172
	ds_bpermute_b32 v181, v157, v173
	s_waitcnt lgkmcnt(4)
	global_store_dwordx4 v[182:183], v[174:177], off
	v_pk_mul_f32 v[162:163], v[30:31], s[100:101]
	v_pk_mul_f32 v[164:165], v[32:33], s[100:101]
	v_pk_mul_f32 v[166:167], v[26:27], s[100:101]
	v_pk_mul_f32 v[168:169], v[28:29], s[100:101]
	v_cvt_pk_bf16_f32 v170, v162, v163
	v_cvt_pk_bf16_f32 v171, v164, v165
	v_cvt_pk_bf16_f32 v172, v166, v167
	v_cvt_pk_bf16_f32 v173, v168, v169
	ds_bpermute_b32 v174, v157, v170
	ds_bpermute_b32 v175, v157, v171
	ds_bpermute_b32 v176, v157, v172
	ds_bpermute_b32 v177, v157, v173
	s_waitcnt lgkmcnt(4)
	global_store_dwordx4 v[182:183], v[178:181], off offset:256
	s_mov_b32 s10, 0x50000
	s_mov_b32 s11, 0
	v_lshl_add_u64 v[182:183], v[184:185], 0, s[10:11]
	v_pk_mul_f32 v[162:163], v[22:23], s[100:101]
	v_pk_mul_f32 v[164:165], v[24:25], s[100:101]
	v_pk_mul_f32 v[166:167], v[18:19], s[100:101]
	v_pk_mul_f32 v[168:169], v[20:21], s[100:101]
	v_cvt_pk_bf16_f32 v170, v162, v163
	v_cvt_pk_bf16_f32 v171, v164, v165
	v_cvt_pk_bf16_f32 v172, v166, v167
	v_cvt_pk_bf16_f32 v173, v168, v169
	ds_bpermute_b32 v178, v157, v170
	ds_bpermute_b32 v179, v157, v171
	ds_bpermute_b32 v180, v157, v172
	ds_bpermute_b32 v181, v157, v173
	s_waitcnt lgkmcnt(4)
; #define GAS __attribute__((address_space(1)))
; __device__ __forceinline__ float sigmoidf_(float x) { return fast_rcp(1.0f + fast_exp2(-x * LOG2E)); }
; __device__ __forceinline__ float siluf_(float x) { return x * sigmoidf_(x); }
; __device__ __forceinline__ v4u tr4(int a, v4u x) { return (v4u){bperm(a, x.x), bperm(a, x.y), bperm(a, x.z), bperm(a, x.w)}; }
; __device__ __forceinline__ v4u pack8(const f32x4& a, const f32x4& b) { return (v4u){pg8::cvt_pk_bf16(a[0], a[1]), pg8::cvt_pk_bf16(a[2], a[3]), pg8::cvt_pk_bf16(b[0], b[1]), pg8::cvt_pk_bf16(b[2], b[3])}; }
;     __device__ __forceinline__ bool operator()(AccT& acc, const Unit& u, int wr, int wc, int fr, int fq) const {
;     ...
;         if (seg == 0 || seg == 1 || seg == 2 || seg >= 6) {
;             bf16* dst = (bf16*)(ws + (seg == 0 ? WS_VR : seg == 1 ? WS_GR : seg == 2 ? WS_QS : WS_GT)); const int ld = seg >= 6 ? 3 * D : D; const int cofs = seg >= 6 ? (seg - 6) * D : 0;
; #pragma unroll
;             for (int ai = 0; ai < 2; ++ai)
; #pragma unroll
;                 for (int m = 0; m < 4; ++m) { const size_t r = (size_t)(pm * 256 + trl0 + ai * 128 + m * 16);
; #pragma unroll
;                     for (int bj = 0; bj < 2; ++bj) { f32x4 v0 = acc[ai][bj][m][0], v1 = acc[ai][bj][m][1];
;                         if (seg == 1) {
; #pragma unroll
;                             for (int e = 0; e < 4; ++e) { v0[e] = siluf_(v0[e]); v1[e] = siluf_(v1[e]); } }
;                         else if (seg == 2) { v0 = v0 * (0.08838834764831845f * LOG2E); v1 = v1 * (0.08838834764831845f * LOG2E); }
;                         else if (seg >= 6) {
; #pragma unroll
;                             for (int e = 0; e < 4; ++e) { v0[e] = sigmoidf_(v0[e]); v1[e] = sigmoidf_(v1[e]); } }
;                         *(GAS v4u*)(dst + r * ld + cofs + colt + bj * 128) = tr4(t.pull, pack8(v0, v1)); } }
	global_store_dwordx4 v[182:183], v[174:177], off
	v_pk_mul_f32 v[162:163], v[14:15], s[100:101]
	v_pk_mul_f32 v[164:165], v[16:17], s[100:101]
	v_pk_mul_f32 v[166:167], v[10:11], s[100:101]
	v_pk_mul_f32 v[168:169], v[12:13], s[100:101]
	v_cvt_pk_bf16_f32 v170, v162, v163
	v_cvt_pk_bf16_f32 v171, v164, v165
	v_cvt_pk_bf16_f32 v172, v166, v167
	v_cvt_pk_bf16_f32 v173, v168, v169
	ds_bpermute_b32 v174, v157, v170
	ds_bpermute_b32 v175, v157, v171
	ds_bpermute_b32 v176, v157, v172
	ds_bpermute_b32 v177, v157, v173
	s_waitcnt lgkmcnt(4)
	global_store_dwordx4 v[182:183], v[178:181], off offset:256
	s_mov_b32 s10, 0x58000
	s_mov_b32 s11, 0
	v_lshl_add_u64 v[182:183], v[184:185], 0, s[10:11]
	v_pk_mul_f32 v[162:163], v[6:7], s[100:101]
	v_pk_mul_f32 v[164:165], v[8:9], s[100:101]
	v_pk_mul_f32 v[166:167], v[2:3], s[100:101]
	v_pk_mul_f32 v[168:169], v[4:5], s[100:101]
	v_cvt_pk_bf16_f32 v170, v162, v163
	v_cvt_pk_bf16_f32 v171, v164, v165
	v_cvt_pk_bf16_f32 v172, v166, v167
	v_cvt_pk_bf16_f32 v173, v168, v169
	ds_bpermute_b32 v178, v157, v170
	ds_bpermute_b32 v179, v157, v171
	ds_bpermute_b32 v180, v157, v172
	ds_bpermute_b32 v181, v157, v173
	s_waitcnt lgkmcnt(4)
	global_store_dwordx4 v[182:183], v[174:177], off
	s_waitcnt lgkmcnt(0)
	global_store_dwordx4 v[182:183], v[178:181], off offset:256
	s_mov_b64 s[12:13], 0
	s_branch .LBB0_902
; #define GAS __attribute__((address_space(1)))
; __device__ __forceinline__ float sigmoidf_(float x) { return fast_rcp(1.0f + fast_exp2(-x * LOG2E)); }
; __device__ __forceinline__ float siluf_(float x) { return x * sigmoidf_(x); }
; __device__ __forceinline__ v4u tr4(int a, v4u x) { return (v4u){bperm(a, x.x), bperm(a, x.y), bperm(a, x.z), bperm(a, x.w)}; }
; __device__ __forceinline__ v4u pack8(const f32x4& a, const f32x4& b) { return (v4u){pg8::cvt_pk_bf16(a[0], a[1]), pg8::cvt_pk_bf16(a[2], a[3]), pg8::cvt_pk_bf16(b[0], b[1]), pg8::cvt_pk_bf16(b[2], b[3])}; }
;     __device__ __forceinline__ bool operator()(AccT& acc, const Unit& u, int wr, int wc, int fr, int fq) const {
;     ...
;         if (seg == 0 || seg == 1 || seg == 2 || seg >= 6) {
;             bf16* dst = (bf16*)(ws + (seg == 0 ? WS_VR : seg == 1 ? WS_GR : seg == 2 ? WS_QS : WS_GT)); const int ld = seg >= 6 ? 3 * D : D; const int cofs = seg >= 6 ? (seg - 6) * D : 0;
; #pragma unroll
;             for (int ai = 0; ai < 2; ++ai)
; #pragma unroll
;                 for (int m = 0; m < 4; ++m) { const size_t r = (size_t)(pm * 256 + trl0 + ai * 128 + m * 16);
; #pragma unroll
;                     for (int bj = 0; bj < 2; ++bj) { f32x4 v0 = acc[ai][bj][m][0], v1 = acc[ai][bj][m][1];
;                         if (seg == 1) {
; #pragma unroll
;                             for (int e = 0; e < 4; ++e) { v0[e] = siluf_(v0[e]); v1[e] = siluf_(v1[e]); } }
;                         else if (seg == 2) { v0 = v0 * (0.08838834764831845f * LOG2E); v1 = v1 * (0.08838834764831845f * LOG2E); }
;                         else if (seg >= 6) {
; #pragma unroll
;                             for (int e = 0; e < 4; ++e) { v0[e] = sigmoidf_(v0[e]); v1[e] = sigmoidf_(v1[e]); } }
;                         *(GAS v4u*)(dst + r * ld + cofs + colt + bj * 128) = tr4(t.pull, pack8(v0, v1)); } }
.Lwin_not_scale:
	s_cmp_lt_u32 s31, 4
	s_cbranch_scc0 .Lwin_not_plain
	s_mov_b32 s10, 0x2e6c0000
	s_waitcnt lgkmcnt(0)
	s_mov_b32 s100, 0xbfb8aa3b
	s_mov_b32 s101, 0xbfb8aa3b
	s_add_u32 s10, s46, s10
	s_addc_u32 s11, s47, 0
	v_lshl_add_u32 v142, s28, 8, v140
	v_ashrrev_i32_e32 v139, 31, v138
	v_lshl_add_u64 v[130:131], v[138:139], 1, s[10:11]
	s_movk_i32 s31, 0x400
	v_mad_i64_i32 v[132:133], s[14:15], s31, v142, 0
	v_lshl_add_u64 v[184:185], v[132:133], 1, v[130:131]
	v_cvt_pk_bf16_f32 v170, v126, v127
	v_cvt_pk_bf16_f32 v171, v128, v129
	v_cvt_pk_bf16_f32 v172, v122, v123
	v_cvt_pk_bf16_f32 v173, v124, v125
	ds_bpermute_b32 v174, v157, v170
	ds_bpermute_b32 v175, v157, v171
	ds_bpermute_b32 v176, v157, v172
	ds_bpermute_b32 v177, v157, v173
	v_cvt_pk_bf16_f32 v170, v118, v119
	v_cvt_pk_bf16_f32 v171, v120, v121
	v_cvt_pk_bf16_f32 v172, v114, v115
	v_cvt_pk_bf16_f32 v173, v116, v117
	ds_bpermute_b32 v178, v157, v170
	ds_bpermute_b32 v179, v157, v171
	ds_bpermute_b32 v180, v157, v172
	ds_bpermute_b32 v181, v157, v173
	s_waitcnt lgkmcnt(4)
	global_store_dwordx4 v[184:185], v[174:177], off
	v_cvt_pk_bf16_f32 v170, v110, v111
	v_cvt_pk_bf16_f32 v171, v112, v113
	v_cvt_pk_bf16_f32 v172, v106, v107
	v_cvt_pk_bf16_f32 v173, v108, v109
	ds_bpermute_b32 v174, v157, v170
	ds_bpermute_b32 v175, v157, v171
	ds_bpermute_b32 v176, v157, v172
	ds_bpermute_b32 v177, v157, v173
	s_waitcnt lgkmcnt(4)
	global_store_dwordx4 v[184:185], v[178:181], off offset:256
	s_mov_b32 s10, 0x8000
	s_mov_b32 s11, 0
	v_lshl_add_u64 v[182:183], v[184:185], 0, s[10:11]
	v_cvt_pk_bf16_f32 v170, v102, v103
	v_cvt_pk_bf16_f32 v171, v104, v105
	v_cvt_pk_bf16_f32 v172, v98, v99
	v_cvt_pk_bf16_f32 v173, v100, v101
	ds_bpermute_b32 v178, v157, v170
	ds_bpermute_b32 v179, v157, v171
	ds_bpermute_b32 v180, v157, v172
	ds_bpermute_b32 v181, v157, v173
	s_waitcnt lgkmcnt(4)
	global_store_dwordx4 v[182:183], v[174:177], off
	v_cvt_pk_bf16_f32 v170, v94, v95
	v_cvt_pk_bf16_f32 v171, v96, v97
	v_cvt_pk_bf16_f32 v172, v90, v91
	v_cvt_pk_bf16_f32 v173, v92, v93
	ds_bpermute_b32 v174, v157, v170
	ds_bpermute_b32 v175, v157, v171
	ds_bpermute_b32 v176, v157, v172
	ds_bpermute_b32 v177, v157, v173
	s_waitcnt lgkmcnt(4)
	global_store_dwordx4 v[182:183], v[178:181], off offset:256
	s_mov_b32 s10, 0x10000
	s_mov_b32 s11, 0
	v_lshl_add_u64 v[182:183], v[184:185], 0, s[10:11]
	v_cvt_pk_bf16_f32 v170, v86, v87
	v_cvt_pk_bf16_f32 v171, v88, v89
	v_cvt_pk_bf16_f32 v172, v82, v83
	v_cvt_pk_bf16_f32 v173, v84, v85
	ds_bpermute_b32 v178, v157, v170
	ds_bpermute_b32 v179, v157, v171
	ds_bpermute_b32 v180, v157, v172
	ds_bpermute_b32 v181, v157, v173
	s_waitcnt lgkmcnt(4)
	global_store_dwordx4 v[182:183], v[174:177], off
	v_cvt_pk_bf16_f32 v170, v78, v79
	v_cvt_pk_bf16_f32 v171, v80, v81
	v_cvt_pk_bf16_f32 v172, v74, v75
	v_cvt_pk_bf16_f32 v173, v76, v77
	ds_bpermute_b32 v174, v157, v170
	ds_bpermute_b32 v175, v157, v171
	ds_bpermute_b32 v176, v157, v172
	ds_bpermute_b32 v177, v157, v173
	s_waitcnt lgkmcnt(4)
	global_store_dwordx4 v[182:183], v[178:181], off offset:256
	s_mov_b32 s10, 0x18000
	s_mov_b32 s11, 0
	v_lshl_add_u64 v[182:183], v[184:185], 0, s[10:11]
	v_cvt_pk_bf16_f32 v170, v70, v71
	v_cvt_pk_bf16_f32 v171, v72, v73
	v_cvt_pk_bf16_f32 v172, v66, v67
	v_cvt_pk_bf16_f32 v173, v68, v69
	ds_bpermute_b32 v178, v157, v170
	ds_bpermute_b32 v179, v157, v171
	ds_bpermute_b32 v180, v157, v172
	ds_bpermute_b32 v181, v157, v173
	s_waitcnt lgkmcnt(4)
	global_store_dwordx4 v[182:183], v[174:177], off
	v_cvt_pk_bf16_f32 v170, v62, v63
	v_cvt_pk_bf16_f32 v171, v64, v65
	v_cvt_pk_bf16_f32 v172, v58, v59
	v_cvt_pk_bf16_f32 v173, v60, v61
	ds_bpermute_b32 v174, v157, v170
	ds_bpermute_b32 v175, v157, v171
	ds_bpermute_b32 v176, v157, v172
	ds_bpermute_b32 v177, v157, v173
	s_waitcnt lgkmcnt(4)
	global_store_dwordx4 v[182:183], v[178:181], off offset:256
	s_mov_b32 s10, 0x40000
	s_mov_b32 s11, 0
	v_lshl_add_u64 v[182:183], v[184:185], 0, s[10:11]
	v_cvt_pk_bf16_f32 v170, v54, v55
	v_cvt_pk_bf16_f32 v171, v56, v57
	v_cvt_pk_bf16_f32 v172, v50, v51
	v_cvt_pk_bf16_f32 v173, v52, v53
	ds_bpermute_b32 v178, v157, v170
	ds_bpermute_b32 v179, v157, v171
	ds_bpermute_b32 v180, v157, v172
	ds_bpermute_b32 v181, v157, v173
	s_waitcnt lgkmcnt(4)
	global_store_dwordx4 v[182:183], v[174:177], off
	v_cvt_pk_bf16_f32 v170, v46, v47
	v_cvt_pk_bf16_f32 v171, v48, v49
	v_cvt_pk_bf16_f32 v172, v42, v43
	v_cvt_pk_bf16_f32 v173, v44, v45
	ds_bpermute_b32 v174, v157, v170
	ds_bpermute_b32 v175, v157, v171
	ds_bpermute_b32 v176, v157, v172
	ds_bpermute_b32 v177, v157, v173
	s_waitcnt lgkmcnt(4)
	global_store_dwordx4 v[182:183], v[178:181], off offset:256
	s_mov_b32 s10, 0x48000
	s_mov_b32 s11, 0
	v_lshl_add_u64 v[182:183], v[184:185], 0, s[10:11]
	v_cvt_pk_bf16_f32 v170, v38, v39
	v_cvt_pk_bf16_f32 v171, v40, v41
	v_cvt_pk_bf16_f32 v172, v34, v35
	v_cvt_pk_bf16_f32 v173, v36, v37
	ds_bpermute_b32 v178, v157, v170
	ds_bpermute_b32 v179, v157, v171
	ds_bpermute_b32 v180, v157, v172
	ds_bpermute_b32 v181, v157, v173
	s_waitcnt lgkmcnt(4)
	global_store_dwordx4 v[182:183], v[174:177], off
	v_cvt_pk_bf16_f32 v170, v30, v31
	v_cvt_pk_bf16_f32 v171, v32, v33
	v_cvt_pk_bf16_f32 v172, v26, v27
	v_cvt_pk_bf16_f32 v173, v28, v29
	ds_bpermute_b32 v174, v157, v170
	ds_bpermute_b32 v175, v157, v171
	ds_bpermute_b32 v176, v157, v172
	ds_bpermute_b32 v177, v157, v173
	s_waitcnt lgkmcnt(4)
	global_store_dwordx4 v[182:183], v[178:181], off offset:256
	s_mov_b32 s10, 0x50000
	s_mov_b32 s11, 0
	v_lshl_add_u64 v[182:183], v[184:185], 0, s[10:11]
	v_cvt_pk_bf16_f32 v170, v22, v23
	v_cvt_pk_bf16_f32 v171, v24, v25
	v_cvt_pk_bf16_f32 v172, v18, v19
	v_cvt_pk_bf16_f32 v173, v20, v21
	ds_bpermute_b32 v178, v157, v170
	ds_bpermute_b32 v179, v157, v171
	ds_bpermute_b32 v180, v157, v172
	ds_bpermute_b32 v181, v157, v173
	s_waitcnt lgkmcnt(4)
	global_store_dwordx4 v[182:183], v[174:177], off
	v_cvt_pk_bf16_f32 v170, v14, v15
	v_cvt_pk_bf16_f32 v171, v16, v17
	v_cvt_pk_bf16_f32 v172, v10, v11
	v_cvt_pk_bf16_f32 v173, v12, v13
	ds_bpermute_b32 v174, v157, v170
	ds_bpermute_b32 v175, v157, v171
	ds_bpermute_b32 v176, v157, v172
	ds_bpermute_b32 v177, v157, v173
	s_waitcnt lgkmcnt(4)
	global_store_dwordx4 v[182:183], v[178:181], off offset:256
	s_mov_b32 s10, 0x58000
	s_mov_b32 s11, 0
	v_lshl_add_u64 v[182:183], v[184:185], 0, s[10:11]
	v_cvt_pk_bf16_f32 v170, v6, v7
	v_cvt_pk_bf16_f32 v171, v8, v9
	v_cvt_pk_bf16_f32 v172, v2, v3
	v_cvt_pk_bf16_f32 v173, v4, v5
	ds_bpermute_b32 v178, v157, v170
	ds_bpermute_b32 v179, v157, v171
	ds_bpermute_b32 v180, v157, v172
	ds_bpermute_b32 v181, v157, v173
	s_waitcnt lgkmcnt(4)
	global_store_dwordx4 v[182:183], v[174:177], off
	s_waitcnt lgkmcnt(0)
	global_store_dwordx4 v[182:183], v[178:181], off offset:256
	s_mov_b64 s[12:13], 0
	s_branch .LBB0_902
